# v63 + P1 forget-gate epilogue: log of a value clamped to [9e-14,1] -- dead denormal/non-finite branches dropped, single-multiply ln2 (13->2 instrs per element) on the workgroups that own the f-gate ti
# baseline (speedup 1.0000x reference)
; DI bf16x8 pack8(const f32x4& a, const f32x4& b) { v4u w; w.x = pk2(a[0], a[1]); w.y = pk2(a[2], a[3]); w.z = pk2(b[0], b[1]); w.w = pk2(b[2], b[3]); return __builtin_bit_cast(bf16x8, w); }
;     DI void operator()(const f32x4 (&acc)[2][2][4][2], const pg8::Unit& u, int wr, int wc, int fr, int fq) const {
;     ...
;             EPI_LOOP_BEGIN
; #pragma unroll
;                 for (int bj = 0; bj < 2; ++bj) { const size_t o = (size_t)row * D + cbase + bj * 128; f32x4 lg[2], kk[2];
; #pragma unroll
;                     for (int n = 0; n < 2; ++n)
; #pragma unroll
;                         for (int e = 0; e < 4; ++e) { const float f = fminf(fmaxf(acc[ai][bj][m][n][e], -30.f), 30.f), lb = lbv[bj][n][e], ef = __expf(-f), sg = 1.f / (1.f + ef), sgn = ef / (1.f + ef);
;                             lg[n][e] = __logf(lb + (1.f - lb) * sg); kk[n][e] = (1.f - lb) * sgn; }
;                     *(f32x4*)(lf + o) = lg[0]; *(f32x4*)(lf + o + 4) = lg[1]; *(bf16x8*)(zq + (size_t)T * D + o) = pack8(kk[0], kk[1]); }
.LBB0_268:
	s_and_b64 vcc, exec, s[6:7]
	s_cbranch_vccz .LBB0_267
	v_ashrrev_i32_e32 v161, 31, v160
	v_lshl_add_u64 v[76:77], v[160:161], 2, s[22:23]
	global_load_dwordx4 v[88:91], v[76:77], off
	global_load_dwordx4 v[80:83], v[76:77], off offset:16
	v_max_f32_e32 v68, v140, v140
	v_max_f32_e32 v69, v141, v141
	v_med3_f32 v141, v68, s68, v188
	v_med3_f32 v162, v69, s68, v188
	v_mul_f32_e32 v141, 0xbfb8aa3b, v141
	v_mul_f32_e32 v163, 0xbfb8aa3b, v162
	s_lshl_b32 s45, s8, 8
	v_exp_f32_e32 v162, v141
	v_exp_f32_e32 v163, v163
	v_add_u32_e32 v140, s45, v175
	v_ashrrev_i32_e32 v141, 31, v140
	v_lshlrev_b64 v[140:141], 11, v[140:141]
	v_lshl_add_u64 v[168:169], v[140:141], 0, v[160:161]
	v_pk_add_f32 v[140:141], v[162:163], 1.0 op_sel_hi:[1,0]
	v_max_f32_e32 v142, v142, v142
	v_rcp_f32_e32 v170, v140
	v_rcp_f32_e32 v171, v141
	v_rcp_f32_e32 v164, v141
	s_nop 0
	v_mul_f32_e32 v165, v163, v164
	v_rcp_f32_e32 v141, v140
	s_nop 0
	v_mul_f32_e32 v164, v162, v141
	v_med3_f32 v142, v142, s68, v188
	v_mul_f32_e32 v142, 0xbfb8aa3b, v142
	v_max_f32_e32 v136, v136, v136
	v_med3_f32 v136, v136, s68, v188
	v_mul_f32_e32 v136, 0xbfb8aa3b, v136
	v_max_f32_e32 v138, v138, v138
	v_max_f32_e32 v139, v139, v139
	v_med3_f32 v138, v138, s68, v188
	s_waitcnt vmcnt(0)
	v_pk_add_f32 v[166:167], v[88:89], 1.0 op_sel_hi:[1,0] neg_lo:[1,0] neg_hi:[1,0]
	v_med3_f32 v139, v139, s68, v188
	v_fma_f32 v140, v170, v166, v88
	v_exp_f32_e32 v170, v142
	v_max_f32_e32 v142, v143, v143
	v_log_f32_e32 v140, v140
	v_fma_f32 v141, v171, v167, v89
	v_med3_f32 v142, v142, s68, v188
	v_mul_f32_e32 v142, 0xbfb8aa3b, v142
	v_exp_f32_e32 v171, v142
	v_log_f32_e32 v141, v141
	v_pk_add_f32 v[190:191], v[170:171], 1.0 op_sel_hi:[1,0]
	v_mul_f32_e32 v140, 0x3f317218, v140
	v_mul_f32_e32 v138, 0xbfb8aa3b, v138
	v_mul_f32_e32 v139, 0xbfb8aa3b, v139
	v_mul_f32_e32 v141, 0x3f317218, v141
	v_rcp_f32_e32 v142, v190
	v_pk_add_f32 v[162:163], v[90:91], 1.0 op_sel_hi:[1,0] neg_lo:[1,0] neg_hi:[1,0]
	v_pk_mul_f32 v[172:173], v[164:165], v[166:167]
	v_fma_f32 v142, v142, v162, v90
	v_exp_f32_e32 v138, v138
	v_exp_f32_e32 v139, v139
	v_log_f32_e32 v142, v142
	global_load_dwordx4 v[68:71], v[76:77], off offset:528
	s_nop 0
	global_load_dwordx4 v[76:79], v[76:77], off offset:512
	v_mul_f32_e32 v142, 0x3f317218, v142
	v_rcp_f32_e32 v143, v191
	s_nop 0
	v_fma_f32 v143, v143, v163, v91
	v_rcp_f32_e32 v164, v191
	s_nop 0
	v_mul_f32_e32 v165, v171, v164
	v_rcp_f32_e32 v164, v190
	s_nop 0
	v_mul_f32_e32 v164, v170, v164
	v_max_f32_e32 v132, v132, v132
	v_exp_f32_e32 v170, v136
	v_max_f32_e32 v136, v137, v137
	v_med3_f32 v136, v136, s68, v188
	v_mul_f32_e32 v136, 0xbfb8aa3b, v136
	v_exp_f32_e32 v171, v136
	v_log_f32_e32 v143, v143
	v_med3_f32 v132, v132, s68, v188
	v_mul_f32_e32 v132, 0xbfb8aa3b, v132
	v_pk_add_f32 v[192:193], v[170:171], 1.0 op_sel_hi:[1,0]
	v_max_f32_e32 v134, v134, v134
	v_med3_f32 v134, v134, s68, v188
	v_mul_f32_e32 v143, 0x3f317218, v143
	v_rcp_f32_e32 v190, v192
	v_pk_add_f32 v[136:137], v[80:81], 1.0 op_sel_hi:[1,0] neg_lo:[1,0] neg_hi:[1,0]
	v_pk_mul_f32 v[194:195], v[164:165], v[162:163]
	v_fma_f32 v190, v190, v136, v80
	v_mul_f32_e32 v134, 0xbfb8aa3b, v134
	v_max_f32_e32 v128, v128, v128
	v_log_f32_e32 v190, v190
	v_med3_f32 v128, v128, s68, v188
	v_mul_f32_e32 v128, 0xbfb8aa3b, v128
	v_mul_f32_e32 v164, 0x3f317218, v190
	v_mov_b32_e32 v190, v164
	v_rcp_f32_e32 v164, v193
	s_nop 0
	v_fma_f32 v164, v164, v137, v81
	v_rcp_f32_e32 v165, v193
	s_nop 0
	v_mul_f32_e32 v171, v171, v165
	v_rcp_f32_e32 v165, v192
	s_nop 0
	v_mul_f32_e32 v170, v170, v165
	v_log_f32_e32 v164, v164
	v_pk_add_f32 v[196:197], v[138:139], 1.0 op_sel_hi:[1,0]
	v_max_f32_e32 v130, v130, v130
	v_med3_f32 v130, v130, s68, v188
	v_mul_f32_e32 v130, 0xbfb8aa3b, v130
	v_mul_f32_e32 v193, 0x3f317218, v164
	v_rcp_f32_e32 v191, v196
	v_pk_add_f32 v[164:165], v[82:83], 1.0 op_sel_hi:[1,0] neg_lo:[1,0] neg_hi:[1,0]
	v_pk_mul_f32 v[198:199], v[170:171], v[136:137]
	v_fma_f32 v191, v191, v164, v82
	v_max_f32_e32 v124, v124, v124
	v_med3_f32 v124, v124, s68, v188
	v_log_f32_e32 v192, v191
	v_mov_b32_e32 v191, v193
	v_mul_f32_e32 v124, 0xbfb8aa3b, v124
	v_max_f32_e32 v126, v126, v126
	v_mul_f32_e32 v170, 0x3f317218, v192
	v_mov_b32_e32 v192, v170
	v_rcp_f32_e32 v170, v197
	s_nop 0
	v_mul_f32_e32 v139, v139, v170
	v_rcp_f32_e32 v171, v196
	s_nop 0
	v_mul_f32_e32 v138, v138, v171
	v_rcp_f32_e32 v193, v197
	s_nop 0
	v_fma_f32 v193, v193, v165, v83
	v_pk_mul_f32 v[196:197], v[138:139], v[164:165]
	v_lshl_add_u64 v[170:171], v[168:169], 2, s[18:19]
	v_log_f32_e32 v193, v193
	v_exp_f32_e32 v200, v132
	v_max_f32_e32 v132, v133, v133
	v_med3_f32 v132, v132, s68, v188
	v_mul_f32_e32 v132, 0xbfb8aa3b, v132
	v_exp_f32_e32 v201, v132
	v_med3_f32 v126, v126, s68, v188
	v_mul_f32_e32 v138, 0x3f317218, v193
	v_mov_b32_e32 v193, v138
	global_store_dwordx4 v[170:171], v[140:143], off
	global_store_dwordx4 v[170:171], v[190:193], off offset:16
	v_mul_f32_e32 v126, 0xbfb8aa3b, v126
	v_pk_add_f32 v[140:141], v[200:201], 1.0 op_sel_hi:[1,0]
	v_cvt_pk_bf16_f32 v190, v172, v173
	v_cvt_pk_bf16_f32 v191, v194, v195
	v_cvt_pk_bf16_f32 v192, v198, v199
	v_cvt_pk_bf16_f32 v193, v196, v197
	v_rcp_f32_e32 v132, v140
	s_waitcnt vmcnt(2)
; DI bf16x8 pack8(const f32x4& a, const f32x4& b) { v4u w; w.x = pk2(a[0], a[1]); w.y = pk2(a[2], a[3]); w.z = pk2(b[0], b[1]); w.w = pk2(b[2], b[3]); return __builtin_bit_cast(bf16x8, w); }
;     DI void operator()(const f32x4 (&acc)[2][2][4][2], const pg8::Unit& u, int wr, int wc, int fr, int fq) const {
;     ...
;             EPI_LOOP_BEGIN
; #pragma unroll
;                 for (int bj = 0; bj < 2; ++bj) { const size_t o = (size_t)row * D + cbase + bj * 128; f32x4 lg[2], kk[2];
; #pragma unroll
;                     for (int n = 0; n < 2; ++n)
; #pragma unroll
;                         for (int e = 0; e < 4; ++e) { const float f = fminf(fmaxf(acc[ai][bj][m][n][e], -30.f), 30.f), lb = lbv[bj][n][e], ef = __expf(-f), sg = 1.f / (1.f + ef), sgn = ef / (1.f + ef);
;                             lg[n][e] = __logf(lb + (1.f - lb) * sg); kk[n][e] = (1.f - lb) * sgn; }
;                     *(f32x4*)(lf + o) = lg[0]; *(f32x4*)(lf + o + 4) = lg[1]; *(bf16x8*)(zq + (size_t)T * D + o) = pack8(kk[0], kk[1]); }
	v_pk_add_f32 v[138:139], v[76:77], 1.0 op_sel_hi:[1,0] neg_lo:[1,0] neg_hi:[1,0]
	v_lshl_add_u64 v[142:143], v[168:169], 1, s[42:43]
	v_fma_f32 v132, v132, v138, v76
	s_nop 0
	s_nop 0
	v_log_f32_e32 v132, v132
	global_store_dwordx4 v[142:143], v[190:193], off
	v_max_f32_e32 v120, v120, v120
	v_med3_f32 v120, v120, s68, v188
	v_mul_f32_e32 v120, 0xbfb8aa3b, v120
	v_mul_f32_e32 v132, 0x3f317218, v132
	v_rcp_f32_e32 v133, v141
	s_nop 0
	v_mul_f32_e32 v169, v201, v133
	v_max_f32_e32 v122, v122, v122
	v_max_f32_e32 v123, v123, v123
	v_exp_f32_e32 v172, v134
	v_max_f32_e32 v134, v135, v135
	v_med3_f32 v134, v134, s68, v188
	v_mul_f32_e32 v134, 0xbfb8aa3b, v134
	v_exp_f32_e32 v173, v134
	v_rcp_f32_e32 v141, v141
	s_nop 0
	v_fma_f32 v141, v141, v139, v77
	v_pk_add_f32 v[190:191], v[172:173], 1.0 op_sel_hi:[1,0]
	v_med3_f32 v122, v122, s68, v188
	v_rcp_f32_e32 v133, v140
	s_nop 0
	v_mul_f32_e32 v168, v200, v133
	v_log_f32_e32 v192, v141
	v_rcp_f32_e32 v134, v190
	v_pk_add_f32 v[140:141], v[78:79], 1.0 op_sel_hi:[1,0] neg_lo:[1,0] neg_hi:[1,0]
	v_fma_f32 v134, v134, v140, v78
	v_log_f32_e32 v134, v134
	v_pk_mul_f32 v[168:169], v[168:169], v[138:139]
	v_mul_f32_e32 v133, 0x3f317218, v192
	v_med3_f32 v123, v123, s68, v188
	v_mul_f32_e32 v122, 0xbfb8aa3b, v122
	v_mul_f32_e32 v134, 0x3f317218, v134
	v_rcp_f32_e32 v135, v191
	s_nop 0
	v_mul_f32_e32 v173, v173, v135
	v_mul_f32_e32 v123, 0xbfb8aa3b, v123
	v_rcp_f32_e32 v135, v190
	s_nop 0
	v_mul_f32_e32 v172, v172, v135
	v_rcp_f32_e32 v191, v191
	s_nop 0
	v_fma_f32 v191, v191, v141, v79
	v_pk_mul_f32 v[172:173], v[172:173], v[140:141]
	v_exp_f32_e32 v122, v122
	v_exp_f32_e32 v192, v128
	v_max_f32_e32 v128, v129, v129
	v_med3_f32 v128, v128, s68, v188
	v_mul_f32_e32 v128, 0xbfb8aa3b, v128
	v_exp_f32_e32 v193, v128
	v_log_f32_e32 v191, v191
	v_exp_f32_e32 v123, v123
	v_max_f32_e32 v116, v116, v116
	v_pk_add_f32 v[194:195], v[192:193], 1.0 op_sel_hi:[1,0]
	v_rcp_f32_e32 v135, v194
	v_pk_add_f32 v[128:129], v[68:69], 1.0 op_sel_hi:[1,0] neg_lo:[1,0] neg_hi:[1,0]
	v_fma_f32 v135, v135, v128, v68
	v_med3_f32 v116, v116, s68, v188
	v_mul_f32_e32 v116, 0xbfb8aa3b, v116
	v_log_f32_e32 v196, v135
	v_mul_f32_e32 v135, 0x3f317218, v191
	v_max_f32_e32 v118, v118, v118
	v_med3_f32 v118, v118, s68, v188
	v_mul_f32_e32 v190, 0x3f317218, v196
	v_rcp_f32_e32 v191, v195
	s_nop 0
	v_mul_f32_e32 v193, v193, v191
	v_mul_f32_e32 v118, 0xbfb8aa3b, v118
	v_rcp_f32_e32 v191, v194
	s_nop 0
	v_mul_f32_e32 v192, v192, v191
	v_rcp_f32_e32 v195, v195
	s_nop 0
	v_fma_f32 v195, v195, v129, v69
	v_max_f32_e32 v112, v112, v112
	v_med3_f32 v112, v112, s68, v188
	v_exp_f32_e32 v196, v130
	v_max_f32_e32 v130, v131, v131
	v_med3_f32 v130, v130, s68, v188
	v_mul_f32_e32 v130, 0xbfb8aa3b, v130
	v_exp_f32_e32 v197, v130
	v_log_f32_e32 v200, v195
	v_pk_mul_f32 v[194:195], v[192:193], v[128:129]
	v_mul_f32_e32 v112, 0xbfb8aa3b, v112
	v_pk_add_f32 v[198:199], v[196:197], 1.0 op_sel_hi:[1,0]
	v_rcp_f32_e32 v191, v198
	v_pk_add_f32 v[130:131], v[70:71], 1.0 op_sel_hi:[1,0] neg_lo:[1,0] neg_hi:[1,0]
	v_fma_f32 v191, v191, v130, v70
	v_max_f32_e32 v114, v114, v114
	v_max_f32_e32 v115, v115, v115
	v_log_f32_e32 v193, v191
	v_mul_f32_e32 v191, 0x3f317218, v200
	v_med3_f32 v114, v114, s68, v188
	v_med3_f32 v115, v115, s68, v188
	v_mul_f32_e32 v192, 0x3f317218, v193
	v_rcp_f32_e32 v193, v199
	s_nop 0
	v_mul_f32_e32 v197, v197, v193
	v_rcp_f32_e32 v200, v198
	s_nop 0
	v_mul_f32_e32 v196, v196, v200
	v_rcp_f32_e32 v201, v199
	s_nop 0
	v_fma_f32 v201, v201, v131, v71
	v_pk_mul_f32 v[196:197], v[196:197], v[130:131]
	v_mul_f32_e32 v114, 0xbfb8aa3b, v114
	v_log_f32_e32 v201, v201
	v_mul_f32_e32 v115, 0xbfb8aa3b, v115
	v_exp_f32_e32 v114, v114
	v_exp_f32_e32 v115, v115
	v_max_f32_e32 v108, v108, v108
	v_mul_f32_e32 v193, 0x3f317218, v201
	global_store_dwordx4 v[170:171], v[132:135], off offset:512
	global_store_dwordx4 v[170:171], v[190:193], off offset:528
	v_exp_f32_e32 v170, v124
	v_max_f32_e32 v124, v125, v125
	v_med3_f32 v124, v124, s68, v188
	v_mul_f32_e32 v124, 0xbfb8aa3b, v124
	v_exp_f32_e32 v171, v124
	v_cvt_pk_bf16_f32 v132, v168, v169
	v_cvt_pk_bf16_f32 v133, v172, v173
	v_cvt_pk_bf16_f32 v134, v194, v195
	v_pk_add_f32 v[168:169], v[170:171], 1.0 op_sel_hi:[1,0]
	v_cvt_pk_bf16_f32 v135, v196, v197
	global_store_dwordx4 v[142:143], v[132:135], off offset:256
	v_add_u32_e32 v124, s45, v178
	v_med3_f32 v108, v108, s68, v188
	v_rcp_f32_e32 v125, v168
	s_nop 0
	v_fma_f32 v125, v125, v166, v88
	v_mul_f32_e32 v108, 0xbfb8aa3b, v108
	v_max_f32_e32 v110, v110, v110
	v_log_f32_e32 v134, v125
	v_ashrrev_i32_e32 v125, 31, v124
	v_lshlrev_b64 v[124:125], 11, v[124:125]
	v_lshl_add_u64 v[132:133], v[124:125], 0, v[160:161]
	v_med3_f32 v110, v110, s68, v188
	v_mul_f32_e32 v110, 0xbfb8aa3b, v110
	v_mul_f32_e32 v124, 0x3f317218, v134
	v_rcp_f32_e32 v125, v169
	s_nop 0
	v_mul_f32_e32 v135, v171, v125
	v_max_f32_e32 v104, v104, v104
	v_med3_f32 v104, v104, s68, v188
	v_rcp_f32_e32 v134, v169
	s_nop 0
	v_fma_f32 v134, v134, v167, v89
	v_mul_f32_e32 v104, 0xbfb8aa3b, v104
	v_max_f32_e32 v106, v106, v106
	v_exp_f32_e32 v142, v126
	v_max_f32_e32 v126, v127, v127
	v_med3_f32 v126, v126, s68, v188
	v_mul_f32_e32 v126, 0xbfb8aa3b, v126
	v_exp_f32_e32 v143, v126
	v_log_f32_e32 v171, v134
	v_rcp_f32_e32 v125, v168
	s_nop 0
	v_mul_f32_e32 v134, v170, v125
	v_pk_mul_f32 v[134:135], v[134:135], v[166:167]
	v_pk_add_f32 v[168:169], v[142:143], 1.0 op_sel_hi:[1,0]
	v_rcp_f32_e32 v126, v168
	s_nop 0
	v_fma_f32 v126, v126, v162, v90
	v_max_f32_e32 v107, v107, v107
	v_log_f32_e32 v126, v126
	v_mul_f32_e32 v125, 0x3f317218, v171
	v_med3_f32 v106, v106, s68, v188
	v_med3_f32 v107, v107, s68, v188
; DI bf16x8 pack8(const f32x4& a, const f32x4& b) { v4u w; w.x = pk2(a[0], a[1]); w.y = pk2(a[2], a[3]); w.z = pk2(b[0], b[1]); w.w = pk2(b[2], b[3]); return __builtin_bit_cast(bf16x8, w); }
;     DI void operator()(const f32x4 (&acc)[2][2][4][2], const pg8::Unit& u, int wr, int wc, int fr, int fq) const {
;     ...
;             EPI_LOOP_BEGIN
; #pragma unroll
;                 for (int bj = 0; bj < 2; ++bj) { const size_t o = (size_t)row * D + cbase + bj * 128; f32x4 lg[2], kk[2];
; #pragma unroll
;                     for (int n = 0; n < 2; ++n)
; #pragma unroll
;                         for (int e = 0; e < 4; ++e) { const float f = fminf(fmaxf(acc[ai][bj][m][n][e], -30.f), 30.f), lb = lbv[bj][n][e], ef = __expf(-f), sg = 1.f / (1.f + ef), sgn = ef / (1.f + ef);
;                             lg[n][e] = __logf(lb + (1.f - lb) * sg); kk[n][e] = (1.f - lb) * sgn; }
;                     *(f32x4*)(lf + o) = lg[0]; *(f32x4*)(lf + o + 4) = lg[1]; *(bf16x8*)(zq + (size_t)T * D + o) = pack8(kk[0], kk[1]); }
	v_mul_f32_e32 v126, 0x3f317218, v126
	v_rcp_f32_e32 v127, v169
	s_nop 0
	v_mul_f32_e32 v143, v143, v127
	v_mul_f32_e32 v106, 0xbfb8aa3b, v106
	v_rcp_f32_e32 v127, v168
	s_nop 0
	v_mul_f32_e32 v142, v142, v127
	v_rcp_f32_e32 v169, v169
	s_nop 0
	v_fma_f32 v169, v169, v163, v91
	v_mul_f32_e32 v107, 0xbfb8aa3b, v107
	v_exp_f32_e32 v106, v106
	v_exp_f32_e32 v170, v120
	v_max_f32_e32 v120, v121, v121
	v_med3_f32 v120, v120, s68, v188
	v_mul_f32_e32 v120, 0xbfb8aa3b, v120
	v_exp_f32_e32 v171, v120
	v_pk_mul_f32 v[120:121], v[142:143], v[162:163]
	v_log_f32_e32 v169, v169
	v_exp_f32_e32 v107, v107
	v_pk_add_f32 v[142:143], v[170:171], 1.0 op_sel_hi:[1,0]
	v_max_f32_e32 v100, v100, v100
	v_rcp_f32_e32 v168, v142
	s_nop 0
	v_fma_f32 v168, v168, v136, v80
	v_log_f32_e32 v168, v168
	v_mul_f32_e32 v127, 0x3f317218, v169
	v_med3_f32 v100, v100, s68, v188
	v_mul_f32_e32 v100, 0xbfb8aa3b, v100
	v_mul_f32_e32 v168, 0x3f317218, v168
	v_rcp_f32_e32 v169, v143
	s_nop 0
	v_mul_f32_e32 v171, v171, v169
	v_max_f32_e32 v102, v102, v102
	v_rcp_f32_e32 v169, v142
	s_nop 0
	v_mul_f32_e32 v170, v170, v169
	v_rcp_f32_e32 v143, v143
	s_nop 0
	v_fma_f32 v143, v143, v137, v81
	v_med3_f32 v102, v102, s68, v188
	v_mul_f32_e32 v102, 0xbfb8aa3b, v102
	v_pk_add_f32 v[172:173], v[122:123], 1.0 op_sel_hi:[1,0]
	v_log_f32_e32 v190, v143
	v_pk_mul_f32 v[142:143], v[170:171], v[136:137]
	v_rcp_f32_e32 v170, v172
	s_nop 0
	v_fma_f32 v170, v170, v164, v82
	v_log_f32_e32 v170, v170
	v_mul_f32_e32 v169, 0x3f317218, v190
	v_max_f32_e32 v96, v96, v96
	v_med3_f32 v96, v96, s68, v188
	v_mul_f32_e32 v170, 0x3f317218, v170
	v_rcp_f32_e32 v171, v173
	s_nop 0
	v_mul_f32_e32 v123, v123, v171
	v_rcp_f32_e32 v190, v172
	s_nop 0
	v_mul_f32_e32 v122, v122, v190
	v_rcp_f32_e32 v191, v173
	s_nop 0
	v_fma_f32 v191, v191, v165, v83
	v_pk_mul_f32 v[172:173], v[122:123], v[164:165]
	v_exp_f32_e32 v190, v116
	v_log_f32_e32 v191, v191
	v_max_f32_e32 v116, v117, v117
	v_med3_f32 v116, v116, s68, v188
	v_mul_f32_e32 v116, 0xbfb8aa3b, v116
	v_mul_f32_e32 v96, 0xbfb8aa3b, v96
	v_mul_f32_e32 v122, 0x3f317218, v191
	v_exp_f32_e32 v191, v116
	v_mov_b32_e32 v171, v122
	v_lshl_add_u64 v[122:123], v[132:133], 2, s[18:19]
	global_store_dwordx4 v[122:123], v[124:127], off
	global_store_dwordx4 v[122:123], v[168:171], off offset:16
	v_max_f32_e32 v98, v98, v98
	v_cvt_pk_bf16_f32 v125, v120, v121
	v_pk_add_f32 v[168:169], v[190:191], 1.0 op_sel_hi:[1,0]
	v_cvt_pk_bf16_f32 v124, v134, v135
	v_cvt_pk_bf16_f32 v126, v142, v143
	v_max_f32_e32 v99, v99, v99
	v_med3_f32 v98, v98, s68, v188
	v_rcp_f32_e32 v116, v168
	s_nop 0
	v_fma_f32 v116, v116, v138, v76
	v_cvt_pk_bf16_f32 v127, v172, v173
	v_lshl_add_u64 v[120:121], v[132:133], 1, s[42:43]
	v_log_f32_e32 v116, v116
	global_store_dwordx4 v[120:121], v[124:127], off
	v_med3_f32 v99, v99, s68, v188
	v_mul_f32_e32 v98, 0xbfb8aa3b, v98
	v_mul_f32_e32 v99, 0xbfb8aa3b, v99
	v_exp_f32_e32 v98, v98
	v_mul_f32_e32 v116, 0x3f317218, v116
	v_rcp_f32_e32 v117, v169
	s_nop 0
	v_mul_f32_e32 v125, v191, v117
	v_exp_f32_e32 v99, v99
	v_max_f32_e32 v92, v92, v92
	v_rcp_f32_e32 v124, v169
	s_nop 0
	v_fma_f32 v124, v124, v139, v77
	v_med3_f32 v92, v92, s68, v188
	v_mul_f32_e32 v92, 0xbfb8aa3b, v92
	v_exp_f32_e32 v126, v118
	v_max_f32_e32 v118, v119, v119
	v_med3_f32 v118, v118, s68, v188
	v_mul_f32_e32 v118, 0xbfb8aa3b, v118
	v_exp_f32_e32 v127, v118
	v_log_f32_e32 v134, v124
	v_rcp_f32_e32 v117, v168
	s_nop 0
	v_mul_f32_e32 v124, v190, v117
	v_pk_mul_f32 v[124:125], v[124:125], v[138:139]
	v_pk_add_f32 v[132:133], v[126:127], 1.0 op_sel_hi:[1,0]
	v_rcp_f32_e32 v118, v132
	s_nop 0
	v_fma_f32 v118, v118, v140, v78
	v_max_f32_e32 v94, v94, v94
	v_log_f32_e32 v118, v118
	v_mul_f32_e32 v117, 0x3f317218, v134
	v_med3_f32 v94, v94, s68, v188
	v_mul_f32_e32 v94, 0xbfb8aa3b, v94
	v_mul_f32_e32 v118, 0x3f317218, v118
	v_rcp_f32_e32 v119, v133
	s_nop 0
	v_mul_f32_e32 v127, v127, v119
	v_max_f32_e32 v84, v84, v84
	v_rcp_f32_e32 v119, v132
	s_nop 0
	v_mul_f32_e32 v126, v126, v119
	v_rcp_f32_e32 v133, v133
	s_nop 0
	v_fma_f32 v133, v133, v141, v79
	v_med3_f32 v84, v84, s68, v188
	v_mul_f32_e32 v84, 0xbfb8aa3b, v84
	v_exp_f32_e32 v134, v112
	v_max_f32_e32 v112, v113, v113
	v_med3_f32 v112, v112, s68, v188
	v_mul_f32_e32 v112, 0xbfb8aa3b, v112
	v_exp_f32_e32 v135, v112
	v_pk_mul_f32 v[112:113], v[126:127], v[140:141]
	v_log_f32_e32 v133, v133
	v_max_f32_e32 v86, v86, v86
	v_pk_add_f32 v[126:127], v[134:135], 1.0 op_sel_hi:[1,0]
	v_max_f32_e32 v87, v87, v87
	v_rcp_f32_e32 v132, v126
	s_nop 0
	v_fma_f32 v132, v132, v128, v68
	v_log_f32_e32 v132, v132
	v_mul_f32_e32 v119, 0x3f317218, v133
	v_med3_f32 v86, v86, s68, v188
	v_med3_f32 v87, v87, s68, v188
	v_mul_f32_e32 v132, 0x3f317218, v132
	v_rcp_f32_e32 v133, v127
	s_nop 0
	v_mul_f32_e32 v135, v135, v133
	v_mul_f32_e32 v86, 0xbfb8aa3b, v86
	v_rcp_f32_e32 v133, v126
	s_nop 0
	v_mul_f32_e32 v134, v134, v133
	v_rcp_f32_e32 v127, v127
	s_nop 0
	v_fma_f32 v127, v127, v129, v69
	v_mul_f32_e32 v87, 0xbfb8aa3b, v87
	v_exp_f32_e32 v86, v86
	v_pk_add_f32 v[142:143], v[114:115], 1.0 op_sel_hi:[1,0]
	v_log_f32_e32 v168, v127
	v_pk_mul_f32 v[126:127], v[134:135], v[128:129]
	v_rcp_f32_e32 v134, v142
	s_nop 0
	v_fma_f32 v134, v134, v130, v70
	v_log_f32_e32 v134, v134
	v_mul_f32_e32 v133, 0x3f317218, v168
	v_exp_f32_e32 v87, v87
	v_max_f32_e32 v72, v72, v72
	v_mul_f32_e32 v134, 0x3f317218, v134
	v_rcp_f32_e32 v135, v143
	s_nop 0
	v_mul_f32_e32 v115, v115, v135
	v_rcp_f32_e32 v168, v142
	s_nop 0
	v_mul_f32_e32 v114, v114, v168
	v_rcp_f32_e32 v169, v143
	s_nop 0
	v_fma_f32 v169, v169, v131, v71
	v_pk_mul_f32 v[142:143], v[114:115], v[130:131]
	v_med3_f32 v72, v72, s68, v188
; DI bf16x8 pack8(const f32x4& a, const f32x4& b) { v4u w; w.x = pk2(a[0], a[1]); w.y = pk2(a[2], a[3]); w.z = pk2(b[0], b[1]); w.w = pk2(b[2], b[3]); return __builtin_bit_cast(bf16x8, w); }
;     DI void operator()(const f32x4 (&acc)[2][2][4][2], const pg8::Unit& u, int wr, int wc, int fr, int fq) const {
;     ...
;             EPI_LOOP_BEGIN
; #pragma unroll
;                 for (int bj = 0; bj < 2; ++bj) { const size_t o = (size_t)row * D + cbase + bj * 128; f32x4 lg[2], kk[2];
; #pragma unroll
;                     for (int n = 0; n < 2; ++n)
; #pragma unroll
;                         for (int e = 0; e < 4; ++e) { const float f = fminf(fmaxf(acc[ai][bj][m][n][e], -30.f), 30.f), lb = lbv[bj][n][e], ef = __expf(-f), sg = 1.f / (1.f + ef), sgn = ef / (1.f + ef);
;                             lg[n][e] = __logf(lb + (1.f - lb) * sg); kk[n][e] = (1.f - lb) * sgn; }
;                     *(f32x4*)(lf + o) = lg[0]; *(f32x4*)(lf + o + 4) = lg[1]; *(bf16x8*)(zq + (size_t)T * D + o) = pack8(kk[0], kk[1]); }
	v_log_f32_e32 v169, v169
	v_mul_f32_e32 v72, 0xbfb8aa3b, v72
	v_max_f32_e32 v74, v74, v74
	v_med3_f32 v74, v74, s68, v188
	v_mul_f32_e32 v74, 0xbfb8aa3b, v74
	v_mul_f32_e32 v114, 0x3f317218, v169
	v_mov_b32_e32 v135, v114
	global_store_dwordx4 v[122:123], v[116:119], off offset:512
	global_store_dwordx4 v[122:123], v[132:135], off offset:528
	v_cvt_pk_bf16_f32 v115, v112, v113
	v_exp_f32_e32 v118, v108
	v_max_f32_e32 v108, v109, v109
	v_med3_f32 v108, v108, s68, v188
	v_mul_f32_e32 v108, 0xbfb8aa3b, v108
	v_exp_f32_e32 v119, v108
	v_cvt_pk_bf16_f32 v114, v124, v125
	v_cvt_pk_bf16_f32 v116, v126, v127
	v_cvt_pk_bf16_f32 v117, v142, v143
	v_pk_add_f32 v[122:123], v[118:119], 1.0 op_sel_hi:[1,0]
	global_store_dwordx4 v[120:121], v[114:117], off offset:256
	v_add_u32_e32 v108, s45, v179
	v_max_f32_e32 v64, v64, v64
	v_med3_f32 v64, v64, s68, v188
	v_rcp_f32_e32 v109, v122
	s_nop 0
	v_fma_f32 v109, v109, v166, v88
	v_mul_f32_e32 v64, 0xbfb8aa3b, v64
	v_max_f32_e32 v66, v66, v66
	v_log_f32_e32 v114, v109
	v_ashrrev_i32_e32 v109, 31, v108
	v_lshlrev_b64 v[108:109], 11, v[108:109]
	v_lshl_add_u64 v[112:113], v[108:109], 0, v[160:161]
	v_max_f32_e32 v67, v67, v67
	v_med3_f32 v66, v66, s68, v188
	v_mul_f32_e32 v108, 0x3f317218, v114
	v_rcp_f32_e32 v109, v123
	s_nop 0
	v_mul_f32_e32 v115, v119, v109
	v_med3_f32 v67, v67, s68, v188
	v_mul_f32_e32 v66, 0xbfb8aa3b, v66
	v_rcp_f32_e32 v114, v123
	s_nop 0
	v_fma_f32 v114, v114, v167, v89
	v_mul_f32_e32 v67, 0xbfb8aa3b, v67
	v_exp_f32_e32 v66, v66
	v_exp_f32_e32 v116, v110
	v_max_f32_e32 v110, v111, v111
	v_med3_f32 v110, v110, s68, v188
	v_mul_f32_e32 v110, 0xbfb8aa3b, v110
	v_exp_f32_e32 v117, v110
	v_log_f32_e32 v120, v114
	v_rcp_f32_e32 v109, v122
	s_nop 0
	v_mul_f32_e32 v114, v118, v109
	v_pk_mul_f32 v[114:115], v[114:115], v[166:167]
	v_pk_add_f32 v[118:119], v[116:117], 1.0 op_sel_hi:[1,0]
	v_rcp_f32_e32 v110, v118
	s_nop 0
	v_fma_f32 v110, v110, v162, v90
	v_exp_f32_e32 v67, v67
	v_log_f32_e32 v110, v110
	v_mul_f32_e32 v109, 0x3f317218, v120
	v_max_f32_e32 v60, v60, v60
	v_med3_f32 v60, v60, s68, v188
	v_mul_f32_e32 v110, 0x3f317218, v110
	v_rcp_f32_e32 v111, v119
	s_nop 0
	v_mul_f32_e32 v117, v117, v111
	v_mul_f32_e32 v60, 0xbfb8aa3b, v60
	v_rcp_f32_e32 v111, v118
	s_nop 0
	v_mul_f32_e32 v116, v116, v111
	v_rcp_f32_e32 v119, v119
	s_nop 0
	v_fma_f32 v119, v119, v163, v91
	v_max_f32_e32 v62, v62, v62
	v_med3_f32 v62, v62, s68, v188
	v_exp_f32_e32 v120, v104
	v_max_f32_e32 v104, v105, v105
	v_med3_f32 v104, v104, s68, v188
	v_mul_f32_e32 v104, 0xbfb8aa3b, v104
	v_exp_f32_e32 v121, v104
	v_log_f32_e32 v122, v119
	v_pk_mul_f32 v[104:105], v[116:117], v[162:163]
	v_mul_f32_e32 v62, 0xbfb8aa3b, v62
	v_pk_add_f32 v[118:119], v[120:121], 1.0 op_sel_hi:[1,0]
	v_rcp_f32_e32 v116, v118
	s_nop 0
	v_fma_f32 v116, v116, v136, v80
	v_max_f32_e32 v56, v56, v56
	v_log_f32_e32 v116, v116
	v_mul_f32_e32 v111, 0x3f317218, v122
	v_med3_f32 v56, v56, s68, v188
	v_mul_f32_e32 v56, 0xbfb8aa3b, v56
	v_mul_f32_e32 v116, 0x3f317218, v116
	v_rcp_f32_e32 v117, v119
	s_nop 0
	v_mul_f32_e32 v121, v121, v117
	v_max_f32_e32 v58, v58, v58
	v_rcp_f32_e32 v117, v118
	s_nop 0
	v_mul_f32_e32 v120, v120, v117
	v_rcp_f32_e32 v119, v119
	s_nop 0
	v_fma_f32 v119, v119, v137, v81
	v_pk_mul_f32 v[120:121], v[120:121], v[136:137]
	v_max_f32_e32 v59, v59, v59
	v_pk_add_f32 v[122:123], v[106:107], 1.0 op_sel_hi:[1,0]
	v_log_f32_e32 v119, v119
	s_nop 0
	v_rcp_f32_e32 v118, v122
	s_nop 0
	v_fma_f32 v118, v118, v164, v82
	v_log_f32_e32 v118, v118
	v_mul_f32_e32 v117, 0x3f317218, v119
	v_med3_f32 v58, v58, s68, v188
	v_med3_f32 v59, v59, s68, v188
	v_mul_f32_e32 v118, 0x3f317218, v118
	v_rcp_f32_e32 v119, v123
	s_nop 0
	v_mul_f32_e32 v107, v107, v119
	v_rcp_f32_e32 v124, v122
	s_nop 0
	v_mul_f32_e32 v106, v106, v124
	v_rcp_f32_e32 v125, v123
	s_nop 0
	v_fma_f32 v125, v125, v165, v83
	v_pk_mul_f32 v[122:123], v[106:107], v[164:165]
	v_exp_f32_e32 v124, v100
	v_log_f32_e32 v125, v125
	v_max_f32_e32 v100, v101, v101
	v_med3_f32 v100, v100, s68, v188
	v_mul_f32_e32 v100, 0xbfb8aa3b, v100
	v_mul_f32_e32 v58, 0xbfb8aa3b, v58
	v_mul_f32_e32 v106, 0x3f317218, v125
	v_exp_f32_e32 v125, v100
	v_mov_b32_e32 v119, v106
	v_lshl_add_u64 v[106:107], v[112:113], 2, s[18:19]
	global_store_dwordx4 v[106:107], v[108:111], off
	global_store_dwordx4 v[106:107], v[116:119], off offset:16
	v_mul_f32_e32 v59, 0xbfb8aa3b, v59
	v_cvt_pk_bf16_f32 v109, v104, v105
	v_pk_add_f32 v[116:117], v[124:125], 1.0 op_sel_hi:[1,0]
	v_cvt_pk_bf16_f32 v108, v114, v115
	v_cvt_pk_bf16_f32 v110, v120, v121
	v_exp_f32_e32 v58, v58
	v_exp_f32_e32 v59, v59
	v_rcp_f32_e32 v100, v116
	s_nop 0
	v_fma_f32 v100, v100, v138, v76
	v_cvt_pk_bf16_f32 v111, v122, v123
	v_lshl_add_u64 v[104:105], v[112:113], 1, s[42:43]
	v_log_f32_e32 v100, v100
	global_store_dwordx4 v[104:105], v[108:111], off
	v_max_f32_e32 v52, v52, v52
	v_med3_f32 v52, v52, s68, v188
	v_mul_f32_e32 v52, 0xbfb8aa3b, v52
	v_max_f32_e32 v54, v54, v54
	v_mul_f32_e32 v100, 0x3f317218, v100
	v_rcp_f32_e32 v101, v117
	s_nop 0
	v_mul_f32_e32 v109, v125, v101
	v_med3_f32 v54, v54, s68, v188
	v_mul_f32_e32 v54, 0xbfb8aa3b, v54
	v_rcp_f32_e32 v108, v117
	s_nop 0
	v_fma_f32 v108, v108, v139, v77
	v_max_f32_e32 v48, v48, v48
	v_med3_f32 v48, v48, s68, v188
	v_exp_f32_e32 v110, v102
	v_max_f32_e32 v102, v103, v103
	v_med3_f32 v102, v102, s68, v188
	v_mul_f32_e32 v102, 0xbfb8aa3b, v102
	v_exp_f32_e32 v111, v102
	v_log_f32_e32 v114, v108
	v_rcp_f32_e32 v101, v116
	s_nop 0
	v_mul_f32_e32 v108, v124, v101
	v_pk_mul_f32 v[108:109], v[108:109], v[138:139]
	v_pk_add_f32 v[112:113], v[110:111], 1.0 op_sel_hi:[1,0]
	v_rcp_f32_e32 v102, v112
	s_nop 0
; DI bf16x8 pack8(const f32x4& a, const f32x4& b) { v4u w; w.x = pk2(a[0], a[1]); w.y = pk2(a[2], a[3]); w.z = pk2(b[0], b[1]); w.w = pk2(b[2], b[3]); return __builtin_bit_cast(bf16x8, w); }
;     DI void operator()(const f32x4 (&acc)[2][2][4][2], const pg8::Unit& u, int wr, int wc, int fr, int fq) const {
;     ...
;             EPI_LOOP_BEGIN
; #pragma unroll
;                 for (int bj = 0; bj < 2; ++bj) { const size_t o = (size_t)row * D + cbase + bj * 128; f32x4 lg[2], kk[2];
; #pragma unroll
;                     for (int n = 0; n < 2; ++n)
; #pragma unroll
;                         for (int e = 0; e < 4; ++e) { const float f = fminf(fmaxf(acc[ai][bj][m][n][e], -30.f), 30.f), lb = lbv[bj][n][e], ef = __expf(-f), sg = 1.f / (1.f + ef), sgn = ef / (1.f + ef);
;                             lg[n][e] = __logf(lb + (1.f - lb) * sg); kk[n][e] = (1.f - lb) * sgn; }
;                     *(f32x4*)(lf + o) = lg[0]; *(f32x4*)(lf + o + 4) = lg[1]; *(bf16x8*)(zq + (size_t)T * D + o) = pack8(kk[0], kk[1]); }
	v_fma_f32 v102, v102, v140, v78
	v_mul_f32_e32 v48, 0xbfb8aa3b, v48
	v_log_f32_e32 v102, v102
	v_mul_f32_e32 v101, 0x3f317218, v114
	v_max_f32_e32 v50, v50, v50
	v_max_f32_e32 v51, v51, v51
	v_mul_f32_e32 v102, 0x3f317218, v102
	v_rcp_f32_e32 v103, v113
	s_nop 0
	v_mul_f32_e32 v111, v111, v103
	v_med3_f32 v50, v50, s68, v188
	v_rcp_f32_e32 v103, v112
	s_nop 0
	v_mul_f32_e32 v110, v110, v103
	v_rcp_f32_e32 v113, v113
	s_nop 0
	v_fma_f32 v113, v113, v141, v79
	v_med3_f32 v51, v51, s68, v188
	v_mul_f32_e32 v50, 0xbfb8aa3b, v50
	v_exp_f32_e32 v114, v96
	v_max_f32_e32 v96, v97, v97
	v_med3_f32 v96, v96, s68, v188
	v_mul_f32_e32 v96, 0xbfb8aa3b, v96
	v_exp_f32_e32 v115, v96
	v_log_f32_e32 v116, v113
	v_pk_mul_f32 v[96:97], v[110:111], v[140:141]
	v_mul_f32_e32 v51, 0xbfb8aa3b, v51
	v_pk_add_f32 v[112:113], v[114:115], 1.0 op_sel_hi:[1,0]
	v_rcp_f32_e32 v110, v112
	s_nop 0
	v_fma_f32 v110, v110, v128, v68
	v_exp_f32_e32 v50, v50
	v_log_f32_e32 v110, v110
	v_mul_f32_e32 v103, 0x3f317218, v116
	v_exp_f32_e32 v51, v51
	v_max_f32_e32 v44, v44, v44
	v_mul_f32_e32 v110, 0x3f317218, v110
	v_rcp_f32_e32 v111, v113
	s_nop 0
	v_mul_f32_e32 v115, v115, v111
	v_med3_f32 v44, v44, s68, v188
	v_rcp_f32_e32 v111, v112
	s_nop 0
	v_mul_f32_e32 v114, v114, v111
	v_rcp_f32_e32 v113, v113
	s_nop 0
	v_fma_f32 v113, v113, v129, v69
	v_pk_mul_f32 v[114:115], v[114:115], v[128:129]
	v_mul_f32_e32 v44, 0xbfb8aa3b, v44
	v_pk_add_f32 v[116:117], v[98:99], 1.0 op_sel_hi:[1,0]
	v_log_f32_e32 v113, v113
	s_nop 0
	v_rcp_f32_e32 v112, v116
	s_nop 0
	v_fma_f32 v112, v112, v130, v70
	v_log_f32_e32 v112, v112
	v_mul_f32_e32 v111, 0x3f317218, v113
	v_max_f32_e32 v46, v46, v46
	v_med3_f32 v46, v46, s68, v188
	v_mul_f32_e32 v112, 0x3f317218, v112
	v_rcp_f32_e32 v113, v117
	s_nop 0
	v_mul_f32_e32 v99, v99, v113
	v_rcp_f32_e32 v118, v116
	s_nop 0
	v_mul_f32_e32 v98, v98, v118
	v_rcp_f32_e32 v119, v117
	s_nop 0
	v_fma_f32 v119, v119, v131, v71
	v_pk_mul_f32 v[116:117], v[98:99], v[130:131]
	v_mul_f32_e32 v46, 0xbfb8aa3b, v46
	v_log_f32_e32 v119, v119
	v_max_f32_e32 v40, v40, v40
	v_med3_f32 v40, v40, s68, v188
	v_mul_f32_e32 v40, 0xbfb8aa3b, v40
	v_max_f32_e32 v42, v42, v42
	v_mul_f32_e32 v98, 0x3f317218, v119
	v_mov_b32_e32 v113, v98
	global_store_dwordx4 v[106:107], v[100:103], off offset:512
	global_store_dwordx4 v[106:107], v[110:113], off offset:528
	v_cvt_pk_bf16_f32 v99, v96, v97
	v_exp_f32_e32 v102, v92
	v_max_f32_e32 v92, v93, v93
	v_med3_f32 v92, v92, s68, v188
	v_mul_f32_e32 v92, 0xbfb8aa3b, v92
	v_exp_f32_e32 v103, v92
	v_cvt_pk_bf16_f32 v98, v108, v109
	v_cvt_pk_bf16_f32 v100, v114, v115
	v_cvt_pk_bf16_f32 v101, v116, v117
	v_pk_add_f32 v[106:107], v[102:103], 1.0 op_sel_hi:[1,0]
	global_store_dwordx4 v[104:105], v[98:101], off offset:256
	v_add_u32_e32 v92, s45, v180
	v_max_f32_e32 v43, v43, v43
	v_med3_f32 v42, v42, s68, v188
	v_rcp_f32_e32 v93, v106
	s_nop 0
	v_fma_f32 v93, v93, v166, v88
	v_med3_f32 v43, v43, s68, v188
	v_mul_f32_e32 v42, 0xbfb8aa3b, v42
	v_log_f32_e32 v98, v93
	v_ashrrev_i32_e32 v93, 31, v92
	v_lshlrev_b64 v[92:93], 11, v[92:93]
	v_lshl_add_u64 v[96:97], v[92:93], 0, v[160:161]
	v_mul_f32_e32 v43, 0xbfb8aa3b, v43
	v_exp_f32_e32 v42, v42
	v_mul_f32_e32 v92, 0x3f317218, v98
	v_rcp_f32_e32 v93, v107
	s_nop 0
	v_mul_f32_e32 v99, v103, v93
	v_exp_f32_e32 v43, v43
	v_max_f32_e32 v36, v36, v36
	v_rcp_f32_e32 v98, v107
	s_nop 0
	v_fma_f32 v98, v98, v167, v89
	v_med3_f32 v36, v36, s68, v188
	v_mul_f32_e32 v36, 0xbfb8aa3b, v36
	v_exp_f32_e32 v100, v94
	v_max_f32_e32 v94, v95, v95
	v_med3_f32 v94, v94, s68, v188
	v_mul_f32_e32 v94, 0xbfb8aa3b, v94
	v_exp_f32_e32 v101, v94
	v_log_f32_e32 v104, v98
	v_rcp_f32_e32 v93, v106
	s_nop 0
	v_mul_f32_e32 v98, v102, v93
	v_pk_mul_f32 v[98:99], v[98:99], v[166:167]
	v_pk_add_f32 v[102:103], v[100:101], 1.0 op_sel_hi:[1,0]
	v_rcp_f32_e32 v94, v102
	s_nop 0
	v_fma_f32 v94, v94, v162, v90
	v_max_f32_e32 v38, v38, v38
	v_log_f32_e32 v94, v94
	v_mul_f32_e32 v93, 0x3f317218, v104
	v_med3_f32 v38, v38, s68, v188
	v_mul_f32_e32 v38, 0xbfb8aa3b, v38
	v_mul_f32_e32 v94, 0x3f317218, v94
	v_rcp_f32_e32 v95, v103
	s_nop 0
	v_mul_f32_e32 v101, v101, v95
	v_max_f32_e32 v32, v32, v32
	v_rcp_f32_e32 v95, v102
	s_nop 0
	v_mul_f32_e32 v100, v100, v95
	v_rcp_f32_e32 v103, v103
	s_nop 0
	v_fma_f32 v103, v103, v163, v91
	v_med3_f32 v32, v32, s68, v188
	v_mul_f32_e32 v32, 0xbfb8aa3b, v32
	v_exp_f32_e32 v104, v84
	v_max_f32_e32 v84, v85, v85
	v_med3_f32 v84, v84, s68, v188
	v_mul_f32_e32 v84, 0xbfb8aa3b, v84
	v_exp_f32_e32 v105, v84
	v_log_f32_e32 v106, v103
	v_pk_mul_f32 v[84:85], v[100:101], v[162:163]
	v_max_f32_e32 v34, v34, v34
	v_pk_add_f32 v[102:103], v[104:105], 1.0 op_sel_hi:[1,0]
	v_rcp_f32_e32 v100, v102
	s_nop 0
	v_fma_f32 v100, v100, v136, v80
	v_max_f32_e32 v35, v35, v35
	v_log_f32_e32 v100, v100
	v_mul_f32_e32 v95, 0x3f317218, v106
	v_med3_f32 v34, v34, s68, v188
	v_med3_f32 v35, v35, s68, v188
	v_mul_f32_e32 v100, 0x3f317218, v100
	v_rcp_f32_e32 v101, v103
	s_nop 0
	v_mul_f32_e32 v105, v105, v101
	v_mul_f32_e32 v34, 0xbfb8aa3b, v34
	v_rcp_f32_e32 v101, v102
	s_nop 0
	v_mul_f32_e32 v104, v104, v101
	v_rcp_f32_e32 v103, v103
	s_nop 0
	v_fma_f32 v103, v103, v137, v81
	v_pk_mul_f32 v[104:105], v[104:105], v[136:137]
	v_mul_f32_e32 v35, 0xbfb8aa3b, v35
	v_pk_add_f32 v[106:107], v[86:87], 1.0 op_sel_hi:[1,0]
	v_log_f32_e32 v103, v103
	s_nop 0
	v_rcp_f32_e32 v102, v106
	s_nop 0
	v_fma_f32 v102, v102, v164, v82
	v_log_f32_e32 v102, v102
	v_mul_f32_e32 v101, 0x3f317218, v103
	v_exp_f32_e32 v34, v34
	v_exp_f32_e32 v35, v35
	v_mul_f32_e32 v102, 0x3f317218, v102
	v_rcp_f32_e32 v103, v107
	s_nop 0
	v_mul_f32_e32 v87, v87, v103
; DI bf16x8 pack8(const f32x4& a, const f32x4& b) { v4u w; w.x = pk2(a[0], a[1]); w.y = pk2(a[2], a[3]); w.z = pk2(b[0], b[1]); w.w = pk2(b[2], b[3]); return __builtin_bit_cast(bf16x8, w); }
;     DI void operator()(const f32x4 (&acc)[2][2][4][2], const pg8::Unit& u, int wr, int wc, int fr, int fq) const {
;     ...
;             EPI_LOOP_BEGIN
; #pragma unroll
;                 for (int bj = 0; bj < 2; ++bj) { const size_t o = (size_t)row * D + cbase + bj * 128; f32x4 lg[2], kk[2];
; #pragma unroll
;                     for (int n = 0; n < 2; ++n)
; #pragma unroll
;                         for (int e = 0; e < 4; ++e) { const float f = fminf(fmaxf(acc[ai][bj][m][n][e], -30.f), 30.f), lb = lbv[bj][n][e], ef = __expf(-f), sg = 1.f / (1.f + ef), sgn = ef / (1.f + ef);
;                             lg[n][e] = __logf(lb + (1.f - lb) * sg); kk[n][e] = (1.f - lb) * sgn; }
;                     *(f32x4*)(lf + o) = lg[0]; *(f32x4*)(lf + o + 4) = lg[1]; *(bf16x8*)(zq + (size_t)T * D + o) = pack8(kk[0], kk[1]); }
	v_rcp_f32_e32 v108, v106
	s_nop 0
	v_mul_f32_e32 v86, v86, v108
	v_rcp_f32_e32 v109, v107
	s_nop 0
	v_fma_f32 v109, v109, v165, v83
	v_pk_mul_f32 v[106:107], v[86:87], v[164:165]
	v_exp_f32_e32 v108, v72
	v_log_f32_e32 v109, v109
	v_max_f32_e32 v72, v73, v73
	v_med3_f32 v72, v72, s68, v188
	v_mul_f32_e32 v72, 0xbfb8aa3b, v72
	v_max_f32_e32 v28, v28, v28
	v_mul_f32_e32 v86, 0x3f317218, v109
	v_exp_f32_e32 v109, v72
	v_mov_b32_e32 v103, v86
	v_lshl_add_u64 v[86:87], v[96:97], 2, s[18:19]
	global_store_dwordx4 v[86:87], v[92:95], off
	global_store_dwordx4 v[86:87], v[100:103], off offset:16
	v_med3_f32 v28, v28, s68, v188
	v_cvt_pk_bf16_f32 v93, v84, v85
	v_pk_add_f32 v[100:101], v[108:109], 1.0 op_sel_hi:[1,0]
	v_cvt_pk_bf16_f32 v92, v98, v99
	v_cvt_pk_bf16_f32 v94, v104, v105
	v_mul_f32_e32 v28, 0xbfb8aa3b, v28
	v_max_f32_e32 v30, v30, v30
	v_rcp_f32_e32 v72, v100
	s_nop 0
	v_fma_f32 v72, v72, v138, v76
	v_cvt_pk_bf16_f32 v95, v106, v107
	v_lshl_add_u64 v[84:85], v[96:97], 1, s[42:43]
	v_log_f32_e32 v72, v72
	global_store_dwordx4 v[84:85], v[92:95], off
	v_med3_f32 v30, v30, s68, v188
	v_mul_f32_e32 v30, 0xbfb8aa3b, v30
	v_max_f32_e32 v24, v24, v24
	v_med3_f32 v24, v24, s68, v188
	v_mul_f32_e32 v72, 0x3f317218, v72
	v_rcp_f32_e32 v73, v101
	s_nop 0
	v_mul_f32_e32 v93, v109, v73
	v_mul_f32_e32 v24, 0xbfb8aa3b, v24
	v_max_f32_e32 v26, v26, v26
	v_rcp_f32_e32 v92, v101
	s_nop 0
	v_fma_f32 v92, v92, v139, v77
	v_max_f32_e32 v27, v27, v27
	v_med3_f32 v26, v26, s68, v188
	v_exp_f32_e32 v94, v74
	v_max_f32_e32 v74, v75, v75
	v_med3_f32 v74, v74, s68, v188
	v_mul_f32_e32 v74, 0xbfb8aa3b, v74
	v_exp_f32_e32 v95, v74
	v_log_f32_e32 v98, v92
	v_rcp_f32_e32 v73, v100
	s_nop 0
	v_mul_f32_e32 v92, v108, v73
	v_pk_mul_f32 v[92:93], v[92:93], v[138:139]
	v_pk_add_f32 v[96:97], v[94:95], 1.0 op_sel_hi:[1,0]
	v_rcp_f32_e32 v74, v96
	s_nop 0
	v_fma_f32 v74, v74, v140, v78
	v_med3_f32 v27, v27, s68, v188
	v_log_f32_e32 v74, v74
	v_mul_f32_e32 v73, 0x3f317218, v98
	v_mul_f32_e32 v26, 0xbfb8aa3b, v26
	v_mul_f32_e32 v27, 0xbfb8aa3b, v27
	v_mul_f32_e32 v74, 0x3f317218, v74
	v_rcp_f32_e32 v75, v97
	s_nop 0
	v_mul_f32_e32 v95, v95, v75
	v_exp_f32_e32 v26, v26
	v_rcp_f32_e32 v75, v96
	s_nop 0
	v_mul_f32_e32 v94, v94, v75
	v_rcp_f32_e32 v97, v97
	s_nop 0
	v_fma_f32 v97, v97, v141, v79
	v_exp_f32_e32 v27, v27
	v_max_f32_e32 v20, v20, v20
	v_exp_f32_e32 v98, v64
	v_max_f32_e32 v64, v65, v65
	v_med3_f32 v64, v64, s68, v188
	v_mul_f32_e32 v64, 0xbfb8aa3b, v64
	v_exp_f32_e32 v99, v64
	v_log_f32_e32 v100, v97
	v_pk_mul_f32 v[64:65], v[94:95], v[140:141]
	v_med3_f32 v20, v20, s68, v188
	v_pk_add_f32 v[96:97], v[98:99], 1.0 op_sel_hi:[1,0]
	v_rcp_f32_e32 v94, v96
	s_nop 0
	v_fma_f32 v94, v94, v128, v68
	v_mul_f32_e32 v20, 0xbfb8aa3b, v20
	v_log_f32_e32 v94, v94
	v_mul_f32_e32 v75, 0x3f317218, v100
	v_max_f32_e32 v22, v22, v22
	v_med3_f32 v22, v22, s68, v188
	v_mul_f32_e32 v94, 0x3f317218, v94
	v_rcp_f32_e32 v95, v97
	s_nop 0
	v_mul_f32_e32 v99, v99, v95
	v_mul_f32_e32 v22, 0xbfb8aa3b, v22
	v_rcp_f32_e32 v95, v96
	s_nop 0
	v_mul_f32_e32 v98, v98, v95
	v_rcp_f32_e32 v97, v97
	s_nop 0
	v_fma_f32 v97, v97, v129, v69
	v_pk_mul_f32 v[98:99], v[98:99], v[128:129]
	v_max_f32_e32 v16, v16, v16
	v_pk_add_f32 v[100:101], v[66:67], 1.0 op_sel_hi:[1,0]
	v_log_f32_e32 v97, v97
	s_nop 0
	v_rcp_f32_e32 v96, v100
	s_nop 0
	v_fma_f32 v96, v96, v130, v70
	v_log_f32_e32 v96, v96
	v_mul_f32_e32 v95, 0x3f317218, v97
	v_med3_f32 v16, v16, s68, v188
	v_mul_f32_e32 v16, 0xbfb8aa3b, v16
	v_mul_f32_e32 v96, 0x3f317218, v96
	v_rcp_f32_e32 v97, v101
	s_nop 0
	v_mul_f32_e32 v67, v67, v97
	v_rcp_f32_e32 v102, v100
	s_nop 0
	v_mul_f32_e32 v66, v66, v102
	v_rcp_f32_e32 v103, v101
	s_nop 0
	v_fma_f32 v103, v103, v131, v71
	v_pk_mul_f32 v[66:67], v[66:67], v[130:131]
	v_max_f32_e32 v18, v18, v18
	v_log_f32_e32 v103, v103
	v_max_f32_e32 v19, v19, v19
	v_med3_f32 v18, v18, s68, v188
	v_med3_f32 v19, v19, s68, v188
	v_mul_f32_e32 v18, 0xbfb8aa3b, v18
	v_mul_f32_e32 v97, 0x3f317218, v103
	global_store_dwordx4 v[86:87], v[72:75], off offset:512
	global_store_dwordx4 v[86:87], v[94:97], off offset:528
	v_exp_f32_e32 v86, v60
	v_max_f32_e32 v60, v61, v61
	v_med3_f32 v60, v60, s68, v188
	v_mul_f32_e32 v60, 0xbfb8aa3b, v60
	v_exp_f32_e32 v87, v60
	v_cvt_pk_bf16_f32 v72, v92, v93
	v_cvt_pk_bf16_f32 v73, v64, v65
	v_cvt_pk_bf16_f32 v75, v66, v67
	v_pk_add_f32 v[92:93], v[86:87], 1.0 op_sel_hi:[1,0]
	v_add_u32_e32 v60, s45, v181
	v_cvt_pk_bf16_f32 v74, v98, v99
	global_store_dwordx4 v[84:85], v[72:75], off offset:256
	v_mul_f32_e32 v19, 0xbfb8aa3b, v19
	v_rcp_f32_e32 v61, v92
	s_nop 0
	v_fma_f32 v61, v61, v166, v88
	v_exp_f32_e32 v18, v18
	v_exp_f32_e32 v19, v19
	v_log_f32_e32 v66, v61
	v_ashrrev_i32_e32 v61, 31, v60
	v_lshlrev_b64 v[60:61], 11, v[60:61]
	v_lshl_add_u64 v[64:65], v[60:61], 0, v[160:161]
	v_max_f32_e32 v12, v12, v12
	v_med3_f32 v12, v12, s68, v188
	v_mul_f32_e32 v60, 0x3f317218, v66
	v_rcp_f32_e32 v61, v93
	s_nop 0
	v_mul_f32_e32 v67, v87, v61
	v_mul_f32_e32 v12, 0xbfb8aa3b, v12
	v_max_f32_e32 v14, v14, v14
	v_rcp_f32_e32 v66, v93
	s_nop 0
	v_fma_f32 v66, v66, v167, v89
	v_med3_f32 v14, v14, s68, v188
	v_mul_f32_e32 v14, 0xbfb8aa3b, v14
	v_exp_f32_e32 v72, v62
	v_max_f32_e32 v62, v63, v63
	v_med3_f32 v62, v62, s68, v188
	v_mul_f32_e32 v62, 0xbfb8aa3b, v62
	v_exp_f32_e32 v73, v62
	v_log_f32_e32 v84, v66
	v_rcp_f32_e32 v61, v92
	s_nop 0
	v_mul_f32_e32 v66, v86, v61
	v_pk_mul_f32 v[66:67], v[66:67], v[166:167]
	v_pk_add_f32 v[74:75], v[72:73], 1.0 op_sel_hi:[1,0]
	v_rcp_f32_e32 v62, v74
	s_nop 0
	v_fma_f32 v62, v62, v162, v90
	v_max_f32_e32 v8, v8, v8
	v_log_f32_e32 v62, v62
	v_mul_f32_e32 v61, 0x3f317218, v84
; DI bf16x8 pack8(const f32x4& a, const f32x4& b) { v4u w; w.x = pk2(a[0], a[1]); w.y = pk2(a[2], a[3]); w.z = pk2(b[0], b[1]); w.w = pk2(b[2], b[3]); return __builtin_bit_cast(bf16x8, w); }
;     DI void operator()(const f32x4 (&acc)[2][2][4][2], const pg8::Unit& u, int wr, int wc, int fr, int fq) const {
;     ...
;             EPI_LOOP_BEGIN
; #pragma unroll
;                 for (int bj = 0; bj < 2; ++bj) { const size_t o = (size_t)row * D + cbase + bj * 128; f32x4 lg[2], kk[2];
; #pragma unroll
;                     for (int n = 0; n < 2; ++n)
; #pragma unroll
;                         for (int e = 0; e < 4; ++e) { const float f = fminf(fmaxf(acc[ai][bj][m][n][e], -30.f), 30.f), lb = lbv[bj][n][e], ef = __expf(-f), sg = 1.f / (1.f + ef), sgn = ef / (1.f + ef);
;                             lg[n][e] = __logf(lb + (1.f - lb) * sg); kk[n][e] = (1.f - lb) * sgn; }
;                     *(f32x4*)(lf + o) = lg[0]; *(f32x4*)(lf + o + 4) = lg[1]; *(bf16x8*)(zq + (size_t)T * D + o) = pack8(kk[0], kk[1]); }
	v_max_f32_e32 v9, v9, v9
	v_med3_f32 v8, v8, s68, v188
	v_mul_f32_e32 v62, 0x3f317218, v62
	v_rcp_f32_e32 v63, v75
	s_nop 0
	v_mul_f32_e32 v73, v73, v63
	v_med3_f32 v9, v9, s68, v188
	v_rcp_f32_e32 v63, v74
	s_nop 0
	v_mul_f32_e32 v72, v72, v63
	v_rcp_f32_e32 v75, v75
	s_nop 0
	v_fma_f32 v75, v75, v163, v91
	v_mul_f32_e32 v8, 0xbfb8aa3b, v8
	v_mul_f32_e32 v9, 0xbfb8aa3b, v9
	v_exp_f32_e32 v84, v56
	v_max_f32_e32 v56, v57, v57
	v_med3_f32 v56, v56, s68, v188
	v_mul_f32_e32 v56, 0xbfb8aa3b, v56
	v_exp_f32_e32 v85, v56
	v_log_f32_e32 v86, v75
	v_pk_mul_f32 v[56:57], v[72:73], v[162:163]
	v_exp_f32_e32 v8, v8
	v_pk_add_f32 v[74:75], v[84:85], 1.0 op_sel_hi:[1,0]
	v_rcp_f32_e32 v72, v74
	s_nop 0
	v_fma_f32 v72, v72, v136, v80
	v_exp_f32_e32 v9, v9
	v_log_f32_e32 v72, v72
	v_mul_f32_e32 v63, 0x3f317218, v86
	v_max_f32_e32 v10, v10, v10
	v_max_f32_e32 v11, v11, v11
	v_mul_f32_e32 v72, 0x3f317218, v72
	v_rcp_f32_e32 v73, v75
	s_nop 0
	v_mul_f32_e32 v85, v85, v73
	v_med3_f32 v10, v10, s68, v188
	v_rcp_f32_e32 v73, v74
	s_nop 0
	v_mul_f32_e32 v84, v84, v73
	v_rcp_f32_e32 v75, v75
	s_nop 0
	v_fma_f32 v75, v75, v137, v81
	v_pk_mul_f32 v[84:85], v[84:85], v[136:137]
	v_med3_f32 v11, v11, s68, v188
	v_pk_add_f32 v[86:87], v[58:59], 1.0 op_sel_hi:[1,0]
	v_log_f32_e32 v75, v75
	s_nop 0
	v_rcp_f32_e32 v74, v86
	s_nop 0
	v_fma_f32 v74, v74, v164, v82
	v_log_f32_e32 v74, v74
	v_mul_f32_e32 v73, 0x3f317218, v75
	v_mul_f32_e32 v10, 0xbfb8aa3b, v10
	v_mul_f32_e32 v11, 0xbfb8aa3b, v11
	v_mul_f32_e32 v74, 0x3f317218, v74
	v_rcp_f32_e32 v75, v87
	s_nop 0
	v_mul_f32_e32 v59, v59, v75
	v_rcp_f32_e32 v92, v86
	s_nop 0
	v_mul_f32_e32 v58, v58, v92
	v_rcp_f32_e32 v93, v87
	s_nop 0
	v_fma_f32 v93, v93, v165, v83
	v_pk_mul_f32 v[86:87], v[58:59], v[164:165]
	v_exp_f32_e32 v92, v52
	v_log_f32_e32 v93, v93
	v_max_f32_e32 v52, v53, v53
	v_med3_f32 v52, v52, s68, v188
	v_mul_f32_e32 v52, 0xbfb8aa3b, v52
	v_exp_f32_e32 v10, v10
	v_mul_f32_e32 v58, 0x3f317218, v93
	v_exp_f32_e32 v93, v52
	v_mov_b32_e32 v75, v58
	v_lshl_add_u64 v[58:59], v[64:65], 2, s[18:19]
	global_store_dwordx4 v[58:59], v[60:63], off
	global_store_dwordx4 v[58:59], v[72:75], off offset:16
	v_exp_f32_e32 v11, v11
	v_cvt_pk_bf16_f32 v61, v56, v57
	v_pk_add_f32 v[72:73], v[92:93], 1.0 op_sel_hi:[1,0]
	v_cvt_pk_bf16_f32 v60, v66, v67
	v_cvt_pk_bf16_f32 v62, v84, v85
	v_max_f32_e32 v4, v4, v4
	v_med3_f32 v4, v4, s68, v188
	v_rcp_f32_e32 v52, v72
	s_nop 0
	v_fma_f32 v52, v52, v138, v76
	v_cvt_pk_bf16_f32 v63, v86, v87
	v_lshl_add_u64 v[56:57], v[64:65], 1, s[42:43]
	v_log_f32_e32 v52, v52
	global_store_dwordx4 v[56:57], v[60:63], off
	v_mul_f32_e32 v4, 0xbfb8aa3b, v4
	v_max_f32_e32 v6, v6, v6
	v_med3_f32 v6, v6, s68, v188
	v_mul_f32_e32 v6, 0xbfb8aa3b, v6
	v_mul_f32_e32 v52, 0x3f317218, v52
	v_rcp_f32_e32 v53, v73
	s_nop 0
	v_mul_f32_e32 v61, v93, v53
	v_max_f32_e32 v0, v0, v0
	v_med3_f32 v0, v0, s68, v188
	v_rcp_f32_e32 v60, v73
	s_nop 0
	v_fma_f32 v60, v60, v139, v77
	v_mul_f32_e32 v0, 0xbfb8aa3b, v0
	v_max_f32_e32 v2, v2, v2
	v_exp_f32_e32 v62, v54
	v_max_f32_e32 v54, v55, v55
	v_med3_f32 v54, v54, s68, v188
	v_mul_f32_e32 v54, 0xbfb8aa3b, v54
	v_exp_f32_e32 v63, v54
	v_log_f32_e32 v66, v60
	v_rcp_f32_e32 v53, v72
	s_nop 0
	v_mul_f32_e32 v60, v92, v53
	v_pk_mul_f32 v[60:61], v[60:61], v[138:139]
	v_pk_add_f32 v[64:65], v[62:63], 1.0 op_sel_hi:[1,0]
	v_rcp_f32_e32 v54, v64
	s_nop 0
	v_fma_f32 v54, v54, v140, v78
	v_med3_f32 v2, v2, s68, v188
	v_log_f32_e32 v54, v54
	v_mul_f32_e32 v53, 0x3f317218, v66
	v_mul_f32_e32 v2, 0xbfb8aa3b, v2
	s_nop 0
	v_mul_f32_e32 v54, 0x3f317218, v54
	v_rcp_f32_e32 v55, v65
	s_nop 0
	v_mul_f32_e32 v63, v63, v55
	v_rcp_f32_e32 v55, v64
	s_nop 0
	v_mul_f32_e32 v62, v62, v55
	v_rcp_f32_e32 v65, v65
	s_nop 0
	v_fma_f32 v65, v65, v141, v79
	s_nop 1
	v_exp_f32_e32 v66, v48
	v_max_f32_e32 v48, v49, v49
	v_med3_f32 v48, v48, s68, v188
	v_mul_f32_e32 v48, 0xbfb8aa3b, v48
	v_exp_f32_e32 v67, v48
	v_log_f32_e32 v72, v65
	v_pk_mul_f32 v[48:49], v[62:63], v[140:141]
	v_pk_add_f32 v[64:65], v[66:67], 1.0 op_sel_hi:[1,0]
	s_nop 0
	v_rcp_f32_e32 v62, v64
	s_nop 0
	v_fma_f32 v62, v62, v128, v68
	v_log_f32_e32 v62, v62
	v_mul_f32_e32 v55, 0x3f317218, v72
	s_nop 1
	v_mul_f32_e32 v62, 0x3f317218, v62
	v_rcp_f32_e32 v63, v65
	s_nop 0
	v_mul_f32_e32 v67, v67, v63
	v_rcp_f32_e32 v63, v64
	s_nop 0
	v_mul_f32_e32 v66, v66, v63
	v_rcp_f32_e32 v65, v65
	s_nop 0
	v_fma_f32 v65, v65, v129, v69
	v_pk_mul_f32 v[66:67], v[66:67], v[128:129]
	s_nop 0
	v_pk_add_f32 v[72:73], v[50:51], 1.0 op_sel_hi:[1,0]
	v_log_f32_e32 v65, v65
	s_nop 0
	v_rcp_f32_e32 v64, v72
	s_nop 0
	v_fma_f32 v64, v64, v130, v70
	v_log_f32_e32 v64, v64
	v_mul_f32_e32 v63, 0x3f317218, v65
	s_nop 1
	v_mul_f32_e32 v64, 0x3f317218, v64
	v_rcp_f32_e32 v65, v73
	s_nop 0
	v_mul_f32_e32 v51, v51, v65
	v_rcp_f32_e32 v74, v72
	s_nop 0
	v_mul_f32_e32 v50, v50, v74
	v_rcp_f32_e32 v75, v73
	s_nop 0
	v_fma_f32 v75, v75, v131, v71
	v_pk_mul_f32 v[72:73], v[50:51], v[130:131]
	s_nop 0
	v_log_f32_e32 v75, v75
	s_nop 1
	v_mul_f32_e32 v50, 0x3f317218, v75
	v_mov_b32_e32 v65, v50
	global_store_dwordx4 v[58:59], v[52:55], off offset:512
	global_store_dwordx4 v[58:59], v[62:65], off offset:528
	v_cvt_pk_bf16_f32 v51, v48, v49
	v_exp_f32_e32 v54, v44
	v_max_f32_e32 v44, v45, v45
	v_med3_f32 v44, v44, s68, v188
	v_mul_f32_e32 v44, 0xbfb8aa3b, v44
	v_exp_f32_e32 v55, v44
	v_cvt_pk_bf16_f32 v50, v60, v61
	v_cvt_pk_bf16_f32 v52, v66, v67
	v_cvt_pk_bf16_f32 v53, v72, v73
	v_pk_add_f32 v[58:59], v[54:55], 1.0 op_sel_hi:[1,0]
	global_store_dwordx4 v[56:57], v[50:53], off offset:256
	v_add_u32_e32 v44, s45, v182
	v_rcp_f32_e32 v45, v58
	s_nop 0
	v_fma_f32 v45, v45, v166, v88
; DI bf16x8 pack8(const f32x4& a, const f32x4& b) { v4u w; w.x = pk2(a[0], a[1]); w.y = pk2(a[2], a[3]); w.z = pk2(b[0], b[1]); w.w = pk2(b[2], b[3]); return __builtin_bit_cast(bf16x8, w); }
;     DI void operator()(const f32x4 (&acc)[2][2][4][2], const pg8::Unit& u, int wr, int wc, int fr, int fq) const {
;     ...
;             EPI_LOOP_BEGIN
; #pragma unroll
;                 for (int bj = 0; bj < 2; ++bj) { const size_t o = (size_t)row * D + cbase + bj * 128; f32x4 lg[2], kk[2];
; #pragma unroll
;                     for (int n = 0; n < 2; ++n)
; #pragma unroll
;                         for (int e = 0; e < 4; ++e) { const float f = fminf(fmaxf(acc[ai][bj][m][n][e], -30.f), 30.f), lb = lbv[bj][n][e], ef = __expf(-f), sg = 1.f / (1.f + ef), sgn = ef / (1.f + ef);
;                             lg[n][e] = __logf(lb + (1.f - lb) * sg); kk[n][e] = (1.f - lb) * sgn; }
;                     *(f32x4*)(lf + o) = lg[0]; *(f32x4*)(lf + o + 4) = lg[1]; *(bf16x8*)(zq + (size_t)T * D + o) = pack8(kk[0], kk[1]); }
	s_nop 1
	v_log_f32_e32 v50, v45
	v_ashrrev_i32_e32 v45, 31, v44
	v_lshlrev_b64 v[44:45], 11, v[44:45]
	v_lshl_add_u64 v[48:49], v[44:45], 0, v[160:161]
	s_nop 1
	v_mul_f32_e32 v44, 0x3f317218, v50
	v_rcp_f32_e32 v45, v59
	s_nop 0
	v_mul_f32_e32 v51, v55, v45
	v_rcp_f32_e32 v50, v59
	s_nop 0
	v_fma_f32 v50, v50, v167, v89
	s_nop 1
	v_exp_f32_e32 v52, v46
	v_max_f32_e32 v46, v47, v47
	v_med3_f32 v46, v46, s68, v188
	v_mul_f32_e32 v46, 0xbfb8aa3b, v46
	v_exp_f32_e32 v53, v46
	v_log_f32_e32 v56, v50
	v_rcp_f32_e32 v45, v58
	s_nop 0
	v_mul_f32_e32 v50, v54, v45
	v_pk_mul_f32 v[50:51], v[50:51], v[166:167]
	v_pk_add_f32 v[54:55], v[52:53], 1.0 op_sel_hi:[1,0]
	v_rcp_f32_e32 v46, v54
	s_nop 0
	v_fma_f32 v46, v46, v162, v90
	s_nop 0
	v_log_f32_e32 v46, v46
	v_mul_f32_e32 v45, 0x3f317218, v56
	s_nop 1
	v_mul_f32_e32 v46, 0x3f317218, v46
	v_rcp_f32_e32 v47, v55
	s_nop 0
	v_mul_f32_e32 v53, v53, v47
	v_rcp_f32_e32 v47, v54
	s_nop 0
	v_mul_f32_e32 v52, v52, v47
	v_rcp_f32_e32 v55, v55
	s_nop 0
	v_fma_f32 v55, v55, v163, v91
	s_nop 1
	v_exp_f32_e32 v56, v40
	v_max_f32_e32 v40, v41, v41
	v_med3_f32 v40, v40, s68, v188
	v_mul_f32_e32 v40, 0xbfb8aa3b, v40
	v_exp_f32_e32 v57, v40
	v_log_f32_e32 v58, v55
	v_pk_mul_f32 v[40:41], v[52:53], v[162:163]
	v_pk_add_f32 v[54:55], v[56:57], 1.0 op_sel_hi:[1,0]
	s_nop 0
	v_rcp_f32_e32 v52, v54
	s_nop 0
	v_fma_f32 v52, v52, v136, v80
	v_log_f32_e32 v52, v52
	v_mul_f32_e32 v47, 0x3f317218, v58
	s_nop 1
	v_mul_f32_e32 v52, 0x3f317218, v52
	v_rcp_f32_e32 v53, v55
	s_nop 0
	v_mul_f32_e32 v57, v57, v53
	v_rcp_f32_e32 v53, v54
	s_nop 0
	v_mul_f32_e32 v56, v56, v53
	v_rcp_f32_e32 v55, v55
	s_nop 0
	v_fma_f32 v55, v55, v137, v81
	v_pk_mul_f32 v[56:57], v[56:57], v[136:137]
	s_nop 0
	v_pk_add_f32 v[58:59], v[42:43], 1.0 op_sel_hi:[1,0]
	v_log_f32_e32 v55, v55
	s_nop 0
	v_rcp_f32_e32 v54, v58
	s_nop 0
	v_fma_f32 v54, v54, v164, v82
	v_log_f32_e32 v54, v54
	v_mul_f32_e32 v53, 0x3f317218, v55
	s_nop 1
	v_mul_f32_e32 v54, 0x3f317218, v54
	v_rcp_f32_e32 v55, v59
	s_nop 0
	v_mul_f32_e32 v43, v43, v55
	v_rcp_f32_e32 v60, v58
	s_nop 0
	v_mul_f32_e32 v42, v42, v60
	v_rcp_f32_e32 v61, v59
	s_nop 0
	v_fma_f32 v61, v61, v165, v83
	v_pk_mul_f32 v[58:59], v[42:43], v[164:165]
	v_exp_f32_e32 v60, v36
	v_log_f32_e32 v61, v61
	v_max_f32_e32 v36, v37, v37
	v_med3_f32 v36, v36, s68, v188
	v_mul_f32_e32 v36, 0xbfb8aa3b, v36
	s_nop 0
	v_mul_f32_e32 v42, 0x3f317218, v61
	v_exp_f32_e32 v61, v36
	v_mov_b32_e32 v55, v42
	v_lshl_add_u64 v[42:43], v[48:49], 2, s[18:19]
	global_store_dwordx4 v[42:43], v[44:47], off
	global_store_dwordx4 v[42:43], v[52:55], off offset:16
	s_nop 0
	v_cvt_pk_bf16_f32 v45, v40, v41
	v_pk_add_f32 v[52:53], v[60:61], 1.0 op_sel_hi:[1,0]
	v_cvt_pk_bf16_f32 v44, v50, v51
	v_cvt_pk_bf16_f32 v46, v56, v57
	v_rcp_f32_e32 v36, v52
	s_nop 0
	v_fma_f32 v36, v36, v138, v76
	v_cvt_pk_bf16_f32 v47, v58, v59
	v_lshl_add_u64 v[40:41], v[48:49], 1, s[42:43]
	v_log_f32_e32 v36, v36
	global_store_dwordx4 v[40:41], v[44:47], off
	s_nop 0
	s_nop 1
	v_mul_f32_e32 v36, 0x3f317218, v36
	v_rcp_f32_e32 v37, v53
	s_nop 0
	v_mul_f32_e32 v45, v61, v37
	v_rcp_f32_e32 v44, v53
	s_nop 0
	v_fma_f32 v44, v44, v139, v77
	s_nop 1
	v_exp_f32_e32 v46, v38
	v_max_f32_e32 v38, v39, v39
	v_med3_f32 v38, v38, s68, v188
	v_mul_f32_e32 v38, 0xbfb8aa3b, v38
	v_exp_f32_e32 v47, v38
	v_log_f32_e32 v50, v44
	v_rcp_f32_e32 v37, v52
	s_nop 0
	v_mul_f32_e32 v44, v60, v37
	v_pk_mul_f32 v[44:45], v[44:45], v[138:139]
	v_pk_add_f32 v[48:49], v[46:47], 1.0 op_sel_hi:[1,0]
	v_rcp_f32_e32 v38, v48
	s_nop 0
	v_fma_f32 v38, v38, v140, v78
	s_nop 0
	v_log_f32_e32 v38, v38
	v_mul_f32_e32 v37, 0x3f317218, v50
	s_nop 1
	v_mul_f32_e32 v38, 0x3f317218, v38
	v_rcp_f32_e32 v39, v49
	s_nop 0
	v_mul_f32_e32 v47, v47, v39
	v_rcp_f32_e32 v39, v48
	s_nop 0
	v_mul_f32_e32 v46, v46, v39
	v_rcp_f32_e32 v49, v49
	s_nop 0
	v_fma_f32 v49, v49, v141, v79
	s_nop 1
	v_exp_f32_e32 v50, v32
	v_max_f32_e32 v32, v33, v33
	v_med3_f32 v32, v32, s68, v188
	v_mul_f32_e32 v32, 0xbfb8aa3b, v32
	v_exp_f32_e32 v51, v32
	v_log_f32_e32 v52, v49
	v_pk_mul_f32 v[32:33], v[46:47], v[140:141]
	v_pk_add_f32 v[48:49], v[50:51], 1.0 op_sel_hi:[1,0]
	s_nop 0
	v_rcp_f32_e32 v46, v48
	s_nop 0
	v_fma_f32 v46, v46, v128, v68
	v_log_f32_e32 v46, v46
	v_mul_f32_e32 v39, 0x3f317218, v52
	s_nop 1
	v_mul_f32_e32 v46, 0x3f317218, v46
	v_rcp_f32_e32 v47, v49
	s_nop 0
	v_mul_f32_e32 v51, v51, v47
	v_rcp_f32_e32 v47, v48
	s_nop 0
	v_mul_f32_e32 v50, v50, v47
	v_rcp_f32_e32 v49, v49
	s_nop 0
	v_fma_f32 v49, v49, v129, v69
	v_pk_mul_f32 v[50:51], v[50:51], v[128:129]
	s_nop 0
	v_pk_add_f32 v[52:53], v[34:35], 1.0 op_sel_hi:[1,0]
	v_log_f32_e32 v49, v49
	s_nop 0
	v_rcp_f32_e32 v48, v52
	s_nop 0
	v_fma_f32 v48, v48, v130, v70
	v_log_f32_e32 v48, v48
	v_mul_f32_e32 v47, 0x3f317218, v49
	s_nop 1
	v_mul_f32_e32 v48, 0x3f317218, v48
	v_rcp_f32_e32 v49, v53
	s_nop 0
	v_mul_f32_e32 v35, v35, v49
	v_rcp_f32_e32 v54, v52
	s_nop 0
	v_mul_f32_e32 v34, v34, v54
	v_rcp_f32_e32 v55, v53
	s_nop 0
	v_fma_f32 v55, v55, v131, v71
	v_pk_mul_f32 v[52:53], v[34:35], v[130:131]
	s_nop 0
	v_log_f32_e32 v55, v55
	s_nop 1
	v_mul_f32_e32 v34, 0x3f317218, v55
	v_mov_b32_e32 v49, v34
	global_store_dwordx4 v[42:43], v[36:39], off offset:512
	global_store_dwordx4 v[42:43], v[46:49], off offset:528
	v_cvt_pk_bf16_f32 v35, v32, v33
	v_exp_f32_e32 v38, v28
	v_max_f32_e32 v28, v29, v29
	v_med3_f32 v28, v28, s68, v188
	v_mul_f32_e32 v28, 0xbfb8aa3b, v28
	v_exp_f32_e32 v39, v28
	v_cvt_pk_bf16_f32 v34, v44, v45
	v_cvt_pk_bf16_f32 v36, v50, v51
	v_cvt_pk_bf16_f32 v37, v52, v53
	v_pk_add_f32 v[42:43], v[38:39], 1.0 op_sel_hi:[1,0]
	global_store_dwordx4 v[40:41], v[34:37], off offset:256
; DI bf16x8 pack8(const f32x4& a, const f32x4& b) { v4u w; w.x = pk2(a[0], a[1]); w.y = pk2(a[2], a[3]); w.z = pk2(b[0], b[1]); w.w = pk2(b[2], b[3]); return __builtin_bit_cast(bf16x8, w); }
;     DI void operator()(const f32x4 (&acc)[2][2][4][2], const pg8::Unit& u, int wr, int wc, int fr, int fq) const {
;     ...
;             EPI_LOOP_BEGIN
; #pragma unroll
;                 for (int bj = 0; bj < 2; ++bj) { const size_t o = (size_t)row * D + cbase + bj * 128; f32x4 lg[2], kk[2];
; #pragma unroll
;                     for (int n = 0; n < 2; ++n)
; #pragma unroll
;                         for (int e = 0; e < 4; ++e) { const float f = fminf(fmaxf(acc[ai][bj][m][n][e], -30.f), 30.f), lb = lbv[bj][n][e], ef = __expf(-f), sg = 1.f / (1.f + ef), sgn = ef / (1.f + ef);
;                             lg[n][e] = __logf(lb + (1.f - lb) * sg); kk[n][e] = (1.f - lb) * sgn; }
;                     *(f32x4*)(lf + o) = lg[0]; *(f32x4*)(lf + o + 4) = lg[1]; *(bf16x8*)(zq + (size_t)T * D + o) = pack8(kk[0], kk[1]); }
	v_add_u32_e32 v28, s45, v183
	v_rcp_f32_e32 v29, v42
	s_nop 0
	v_fma_f32 v29, v29, v166, v88
	s_nop 1
	v_log_f32_e32 v34, v29
	v_ashrrev_i32_e32 v29, 31, v28
	v_lshlrev_b64 v[28:29], 11, v[28:29]
	v_lshl_add_u64 v[32:33], v[28:29], 0, v[160:161]
	s_nop 1
	v_mul_f32_e32 v28, 0x3f317218, v34
	v_rcp_f32_e32 v29, v43
	s_nop 0
	v_mul_f32_e32 v35, v39, v29
	v_rcp_f32_e32 v34, v43
	s_nop 0
	v_fma_f32 v34, v34, v167, v89
	s_nop 1
	v_exp_f32_e32 v36, v30
	v_max_f32_e32 v30, v31, v31
	v_med3_f32 v30, v30, s68, v188
	v_mul_f32_e32 v30, 0xbfb8aa3b, v30
	v_exp_f32_e32 v37, v30
	v_log_f32_e32 v40, v34
	v_rcp_f32_e32 v29, v42
	s_nop 0
	v_mul_f32_e32 v34, v38, v29
	v_pk_mul_f32 v[34:35], v[34:35], v[166:167]
	v_pk_add_f32 v[38:39], v[36:37], 1.0 op_sel_hi:[1,0]
	v_rcp_f32_e32 v30, v38
	s_nop 0
	v_fma_f32 v30, v30, v162, v90
	s_nop 0
	v_log_f32_e32 v30, v30
	v_mul_f32_e32 v29, 0x3f317218, v40
	s_nop 1
	v_mul_f32_e32 v30, 0x3f317218, v30
	v_rcp_f32_e32 v31, v39
	s_nop 0
	v_mul_f32_e32 v37, v37, v31
	v_rcp_f32_e32 v31, v38
	s_nop 0
	v_mul_f32_e32 v36, v36, v31
	v_rcp_f32_e32 v39, v39
	s_nop 0
	v_fma_f32 v39, v39, v163, v91
	s_nop 1
	v_exp_f32_e32 v40, v24
	v_max_f32_e32 v24, v25, v25
	v_med3_f32 v24, v24, s68, v188
	v_mul_f32_e32 v24, 0xbfb8aa3b, v24
	v_exp_f32_e32 v41, v24
	v_log_f32_e32 v42, v39
	v_pk_mul_f32 v[24:25], v[36:37], v[162:163]
	v_pk_add_f32 v[38:39], v[40:41], 1.0 op_sel_hi:[1,0]
	s_nop 0
	v_rcp_f32_e32 v36, v38
	s_nop 0
	v_fma_f32 v36, v36, v136, v80
	v_log_f32_e32 v36, v36
	v_mul_f32_e32 v31, 0x3f317218, v42
	s_nop 1
	v_mul_f32_e32 v36, 0x3f317218, v36
	v_rcp_f32_e32 v37, v39
	s_nop 0
	v_mul_f32_e32 v41, v41, v37
	v_rcp_f32_e32 v37, v38
	s_nop 0
	v_mul_f32_e32 v40, v40, v37
	v_rcp_f32_e32 v39, v39
	s_nop 0
	v_fma_f32 v39, v39, v137, v81
	v_pk_mul_f32 v[40:41], v[40:41], v[136:137]
	s_nop 0
	v_pk_add_f32 v[42:43], v[26:27], 1.0 op_sel_hi:[1,0]
	v_log_f32_e32 v39, v39
	s_nop 0
	v_rcp_f32_e32 v38, v42
	s_nop 0
	v_fma_f32 v38, v38, v164, v82
	v_log_f32_e32 v38, v38
	v_mul_f32_e32 v37, 0x3f317218, v39
	s_nop 1
	v_mul_f32_e32 v38, 0x3f317218, v38
	v_rcp_f32_e32 v39, v43
	s_nop 0
	v_mul_f32_e32 v27, v27, v39
	v_rcp_f32_e32 v44, v42
	s_nop 0
	v_mul_f32_e32 v26, v26, v44
	v_rcp_f32_e32 v45, v43
	s_nop 0
	v_fma_f32 v45, v45, v165, v83
	v_pk_mul_f32 v[42:43], v[26:27], v[164:165]
	v_exp_f32_e32 v44, v20
	v_log_f32_e32 v45, v45
	v_max_f32_e32 v20, v21, v21
	v_med3_f32 v20, v20, s68, v188
	v_mul_f32_e32 v20, 0xbfb8aa3b, v20
	s_nop 0
	v_mul_f32_e32 v26, 0x3f317218, v45
	v_exp_f32_e32 v45, v20
	v_mov_b32_e32 v39, v26
	v_lshl_add_u64 v[26:27], v[32:33], 2, s[18:19]
	global_store_dwordx4 v[26:27], v[28:31], off
	global_store_dwordx4 v[26:27], v[36:39], off offset:16
	s_nop 0
	v_cvt_pk_bf16_f32 v29, v24, v25
	v_pk_add_f32 v[36:37], v[44:45], 1.0 op_sel_hi:[1,0]
	v_cvt_pk_bf16_f32 v28, v34, v35
	v_cvt_pk_bf16_f32 v30, v40, v41
	v_rcp_f32_e32 v20, v36
	s_nop 0
	v_fma_f32 v20, v20, v138, v76
	v_cvt_pk_bf16_f32 v31, v42, v43
	v_lshl_add_u64 v[24:25], v[32:33], 1, s[42:43]
	v_log_f32_e32 v20, v20
	global_store_dwordx4 v[24:25], v[28:31], off
	s_nop 0
	s_nop 1
	v_mul_f32_e32 v20, 0x3f317218, v20
	v_rcp_f32_e32 v21, v37
	s_nop 0
	v_mul_f32_e32 v29, v45, v21
	v_rcp_f32_e32 v28, v37
	s_nop 0
	v_fma_f32 v28, v28, v139, v77
	s_nop 1
	v_exp_f32_e32 v30, v22
	v_max_f32_e32 v22, v23, v23
	v_med3_f32 v22, v22, s68, v188
	v_mul_f32_e32 v22, 0xbfb8aa3b, v22
	v_exp_f32_e32 v31, v22
	v_log_f32_e32 v34, v28
	v_rcp_f32_e32 v21, v36
	s_nop 0
	v_mul_f32_e32 v28, v44, v21
	v_pk_mul_f32 v[28:29], v[28:29], v[138:139]
	v_pk_add_f32 v[32:33], v[30:31], 1.0 op_sel_hi:[1,0]
	v_rcp_f32_e32 v22, v32
	s_nop 0
	v_fma_f32 v22, v22, v140, v78
	s_nop 0
	v_log_f32_e32 v22, v22
	v_mul_f32_e32 v21, 0x3f317218, v34
	s_nop 1
	v_mul_f32_e32 v22, 0x3f317218, v22
	v_rcp_f32_e32 v23, v33
	s_nop 0
	v_mul_f32_e32 v31, v31, v23
	v_rcp_f32_e32 v23, v32
	s_nop 0
	v_mul_f32_e32 v30, v30, v23
	v_rcp_f32_e32 v33, v33
	s_nop 0
	v_fma_f32 v33, v33, v141, v79
	s_nop 1
	v_exp_f32_e32 v34, v16
	v_max_f32_e32 v16, v17, v17
	v_med3_f32 v16, v16, s68, v188
	v_mul_f32_e32 v16, 0xbfb8aa3b, v16
	v_exp_f32_e32 v35, v16
	v_log_f32_e32 v36, v33
	v_pk_mul_f32 v[16:17], v[30:31], v[140:141]
	v_pk_add_f32 v[32:33], v[34:35], 1.0 op_sel_hi:[1,0]
	s_nop 0
	v_rcp_f32_e32 v30, v32
	s_nop 0
	v_fma_f32 v30, v30, v128, v68
	v_log_f32_e32 v30, v30
	v_mul_f32_e32 v23, 0x3f317218, v36
	s_nop 1
	v_mul_f32_e32 v30, 0x3f317218, v30
	v_rcp_f32_e32 v31, v33
	s_nop 0
	v_mul_f32_e32 v35, v35, v31
	v_rcp_f32_e32 v31, v32
	s_nop 0
	v_mul_f32_e32 v34, v34, v31
	v_rcp_f32_e32 v33, v33
	s_nop 0
	v_fma_f32 v33, v33, v129, v69
	v_pk_mul_f32 v[34:35], v[34:35], v[128:129]
	s_nop 0
	v_pk_add_f32 v[36:37], v[18:19], 1.0 op_sel_hi:[1,0]
	v_log_f32_e32 v33, v33
	s_nop 0
	v_rcp_f32_e32 v32, v36
	s_nop 0
	v_fma_f32 v32, v32, v130, v70
	v_log_f32_e32 v32, v32
	v_mul_f32_e32 v31, 0x3f317218, v33
	s_nop 1
	v_mul_f32_e32 v32, 0x3f317218, v32
	v_rcp_f32_e32 v33, v37
	s_nop 0
	v_mul_f32_e32 v19, v19, v33
	v_rcp_f32_e32 v38, v36
	s_nop 0
	v_mul_f32_e32 v18, v18, v38
	v_rcp_f32_e32 v39, v37
	s_nop 0
	v_fma_f32 v39, v39, v131, v71
	v_pk_mul_f32 v[36:37], v[18:19], v[130:131]
	s_nop 0
	v_log_f32_e32 v39, v39
	s_nop 1
	v_mul_f32_e32 v18, 0x3f317218, v39
	v_mov_b32_e32 v33, v18
	global_store_dwordx4 v[26:27], v[20:23], off offset:512
	global_store_dwordx4 v[26:27], v[30:33], off offset:528
	v_cvt_pk_bf16_f32 v19, v16, v17
	v_exp_f32_e32 v22, v12
	v_max_f32_e32 v12, v13, v13
	v_med3_f32 v12, v12, s68, v188
	v_mul_f32_e32 v12, 0xbfb8aa3b, v12
	v_exp_f32_e32 v23, v12
	v_cvt_pk_bf16_f32 v18, v28, v29
	v_cvt_pk_bf16_f32 v20, v34, v35
; DI bf16x8 pack8(const f32x4& a, const f32x4& b) { v4u w; w.x = pk2(a[0], a[1]); w.y = pk2(a[2], a[3]); w.z = pk2(b[0], b[1]); w.w = pk2(b[2], b[3]); return __builtin_bit_cast(bf16x8, w); }
;     DI void operator()(const f32x4 (&acc)[2][2][4][2], const pg8::Unit& u, int wr, int wc, int fr, int fq) const {
;     ...
;             EPI_LOOP_BEGIN
; #pragma unroll
;                 for (int bj = 0; bj < 2; ++bj) { const size_t o = (size_t)row * D + cbase + bj * 128; f32x4 lg[2], kk[2];
; #pragma unroll
;                     for (int n = 0; n < 2; ++n)
; #pragma unroll
;                         for (int e = 0; e < 4; ++e) { const float f = fminf(fmaxf(acc[ai][bj][m][n][e], -30.f), 30.f), lb = lbv[bj][n][e], ef = __expf(-f), sg = 1.f / (1.f + ef), sgn = ef / (1.f + ef);
;                             lg[n][e] = __logf(lb + (1.f - lb) * sg); kk[n][e] = (1.f - lb) * sgn; }
;                     *(f32x4*)(lf + o) = lg[0]; *(f32x4*)(lf + o + 4) = lg[1]; *(bf16x8*)(zq + (size_t)T * D + o) = pack8(kk[0], kk[1]); }
	v_cvt_pk_bf16_f32 v21, v36, v37
	v_pk_add_f32 v[26:27], v[22:23], 1.0 op_sel_hi:[1,0]
	global_store_dwordx4 v[24:25], v[18:21], off offset:256
	v_add_u32_e32 v12, s45, v184
	v_rcp_f32_e32 v13, v26
	s_nop 0
	v_fma_f32 v13, v13, v166, v88
	s_nop 1
	v_log_f32_e32 v18, v13
	v_ashrrev_i32_e32 v13, 31, v12
	v_lshlrev_b64 v[12:13], 11, v[12:13]
	v_lshl_add_u64 v[16:17], v[12:13], 0, v[160:161]
	s_nop 1
	v_mul_f32_e32 v12, 0x3f317218, v18
	v_rcp_f32_e32 v13, v27
	s_nop 0
	v_mul_f32_e32 v19, v23, v13
	v_rcp_f32_e32 v18, v27
	s_nop 0
	v_fma_f32 v18, v18, v167, v89
	s_nop 1
	v_exp_f32_e32 v20, v14
	v_max_f32_e32 v14, v15, v15
	v_med3_f32 v14, v14, s68, v188
	v_mul_f32_e32 v14, 0xbfb8aa3b, v14
	v_exp_f32_e32 v21, v14
	v_log_f32_e32 v24, v18
	v_rcp_f32_e32 v13, v26
	s_nop 0
	v_mul_f32_e32 v18, v22, v13
	v_pk_mul_f32 v[18:19], v[18:19], v[166:167]
	v_pk_add_f32 v[22:23], v[20:21], 1.0 op_sel_hi:[1,0]
	v_rcp_f32_e32 v14, v22
	s_nop 0
	v_fma_f32 v14, v14, v162, v90
	s_nop 0
	v_log_f32_e32 v14, v14
	v_mul_f32_e32 v13, 0x3f317218, v24
	s_nop 1
	v_mul_f32_e32 v14, 0x3f317218, v14
	v_rcp_f32_e32 v15, v23
	s_nop 0
	v_mul_f32_e32 v21, v21, v15
	v_rcp_f32_e32 v15, v22
	s_nop 0
	v_mul_f32_e32 v20, v20, v15
	v_rcp_f32_e32 v23, v23
	v_pk_add_f32 v[24:25], v[8:9], 1.0 op_sel_hi:[1,0]
	v_fmac_f32_e32 v91, v23, v163
	v_pk_mul_f32 v[20:21], v[20:21], v[162:163]
	s_nop 0
	v_log_f32_e32 v23, v91
	v_rcp_f32_e32 v22, v24
	s_nop 0
	v_fma_f32 v22, v22, v136, v80
	v_log_f32_e32 v22, v22
	s_nop 1
	v_mul_f32_e32 v15, 0x3f317218, v23
	s_nop 1
	v_mul_f32_e32 v22, 0x3f317218, v22
	v_rcp_f32_e32 v23, v25
	s_nop 0
	v_mul_f32_e32 v9, v9, v23
	v_rcp_f32_e32 v23, v24
	s_nop 0
	v_mul_f32_e32 v8, v8, v23
	v_rcp_f32_e32 v25, v25
	s_nop 0
	v_fma_f32 v25, v25, v137, v81
	s_nop 1
	v_pk_mul_f32 v[26:27], v[8:9], v[136:137]
	v_pk_add_f32 v[8:9], v[10:11], 1.0 op_sel_hi:[1,0]
	v_log_f32_e32 v25, v25
	s_nop 0
	v_rcp_f32_e32 v24, v8
	s_nop 0
	v_fma_f32 v24, v24, v164, v82
	v_log_f32_e32 v24, v24
	v_mul_f32_e32 v23, 0x3f317218, v25
	s_nop 1
	v_mul_f32_e32 v24, 0x3f317218, v24
	v_rcp_f32_e32 v28, v8
	s_nop 0
	v_mul_f32_e32 v8, v10, v28
	v_rcp_f32_e32 v29, v9
	s_nop 0
	v_fmac_f32_e32 v83, v29, v165
	v_rcp_f32_e32 v25, v9
	s_nop 0
	v_mul_f32_e32 v9, v11, v25
	v_pk_mul_f32 v[10:11], v[8:9], v[164:165]
	v_log_f32_e32 v29, v83
	v_exp_f32_e32 v28, v4
	v_max_f32_e32 v4, v5, v5
	v_med3_f32 v4, v4, s68, v188
	v_mul_f32_e32 v4, 0xbfb8aa3b, v4
	v_mul_f32_e32 v8, 0x3f317218, v29
	v_exp_f32_e32 v29, v4
	v_mov_b32_e32 v25, v8
	v_lshl_add_u64 v[8:9], v[16:17], 2, s[18:19]
	global_store_dwordx4 v[8:9], v[12:15], off
	global_store_dwordx4 v[8:9], v[22:25], off offset:16
	s_nop 0
	v_cvt_pk_bf16_f32 v12, v18, v19
	v_pk_add_f32 v[22:23], v[28:29], 1.0 op_sel_hi:[1,0]
	v_cvt_pk_bf16_f32 v13, v20, v21
	v_cvt_pk_bf16_f32 v14, v26, v27
	v_rcp_f32_e32 v4, v22
	s_nop 0
	v_fma_f32 v4, v4, v138, v76
	v_cvt_pk_bf16_f32 v15, v10, v11
	v_lshl_add_u64 v[10:11], v[16:17], 1, s[42:43]
	v_log_f32_e32 v4, v4
	global_store_dwordx4 v[10:11], v[12:15], off
	s_nop 0
	s_nop 1
	v_mul_f32_e32 v4, 0x3f317218, v4
	v_rcp_f32_e32 v5, v23
	s_nop 0
	v_mul_f32_e32 v13, v29, v5
	v_rcp_f32_e32 v12, v23
	s_nop 0
	v_fma_f32 v12, v12, v139, v77
	s_nop 1
	v_exp_f32_e32 v14, v6
	v_max_f32_e32 v6, v7, v7
	v_med3_f32 v6, v6, s68, v188
	v_mul_f32_e32 v6, 0xbfb8aa3b, v6
	v_exp_f32_e32 v15, v6
	v_log_f32_e32 v18, v12
	v_rcp_f32_e32 v5, v22
	s_nop 0
	v_mul_f32_e32 v12, v28, v5
	v_pk_mul_f32 v[12:13], v[12:13], v[138:139]
	v_pk_add_f32 v[16:17], v[14:15], 1.0 op_sel_hi:[1,0]
	v_rcp_f32_e32 v6, v16
	s_nop 0
	v_fma_f32 v6, v6, v140, v78
	s_nop 0
	v_log_f32_e32 v6, v6
	v_mul_f32_e32 v5, 0x3f317218, v18
	s_nop 1
	v_mul_f32_e32 v6, 0x3f317218, v6
	v_rcp_f32_e32 v7, v17
	s_nop 0
	v_mul_f32_e32 v15, v15, v7
	v_rcp_f32_e32 v7, v16
	s_nop 0
	v_mul_f32_e32 v14, v14, v7
	v_rcp_f32_e32 v17, v17
	v_exp_f32_e32 v18, v0
	v_max_f32_e32 v0, v1, v1
	v_med3_f32 v0, v0, s68, v188
	v_mul_f32_e32 v0, 0xbfb8aa3b, v0
	v_fmac_f32_e32 v79, v17, v141
	v_exp_f32_e32 v19, v0
	v_pk_mul_f32 v[14:15], v[14:15], v[140:141]
	s_nop 0
	v_log_f32_e32 v20, v79
	v_pk_add_f32 v[16:17], v[18:19], 1.0 op_sel_hi:[1,0]
	v_rcp_f32_e32 v1, v16
	s_nop 0
	v_fma_f32 v1, v1, v128, v68
	s_nop 0
	v_log_f32_e32 v1, v1
	v_mul_f32_e32 v0, 0x3f317218, v20
	v_mov_b32_e32 v7, v0
	s_nop 1
	v_mul_f32_e32 v0, 0x3f317218, v1
	v_rcp_f32_e32 v1, v17
	s_nop 0
	v_mul_f32_e32 v19, v19, v1
	v_rcp_f32_e32 v1, v16
	s_nop 0
	v_mul_f32_e32 v18, v18, v1
	v_rcp_f32_e32 v17, v17
	s_nop 0
	v_fma_f32 v17, v17, v129, v69
	s_nop 1
	v_exp_f32_e32 v20, v2
	v_max_f32_e32 v2, v3, v3
	v_med3_f32 v2, v2, s68, v188
	v_mul_f32_e32 v2, 0xbfb8aa3b, v2
	v_exp_f32_e32 v21, v2
	v_log_f32_e32 v22, v17
	v_pk_mul_f32 v[16:17], v[18:19], v[128:129]
	v_pk_add_f32 v[18:19], v[20:21], 1.0 op_sel_hi:[1,0]
	s_nop 0
	v_rcp_f32_e32 v2, v18
	s_nop 0
	v_fma_f32 v2, v2, v130, v70
	v_log_f32_e32 v2, v2
	v_mul_f32_e32 v1, 0x3f317218, v22
	s_nop 1
	v_mul_f32_e32 v2, 0x3f317218, v2
	v_rcp_f32_e32 v22, v18
	s_nop 0
	v_mul_f32_e32 v18, v20, v22
	v_rcp_f32_e32 v23, v19
	s_nop 0
	v_fmac_f32_e32 v71, v23, v131
	v_rcp_f32_e32 v3, v19
	s_nop 0
	v_mul_f32_e32 v19, v21, v3
	v_pk_mul_f32 v[18:19], v[18:19], v[130:131]
	v_log_f32_e32 v23, v71
	s_nop 1
	v_mul_f32_e32 v3, 0x3f317218, v23
	global_store_dwordx4 v[8:9], v[4:7], off offset:512
	global_store_dwordx4 v[8:9], v[0:3], off offset:528
	s_nop 1
	v_cvt_pk_bf16_f32 v0, v12, v13
	v_cvt_pk_bf16_f32 v1, v14, v15
	v_cvt_pk_bf16_f32 v2, v16, v17
	v_cvt_pk_bf16_f32 v3, v18, v19
	global_store_dwordx4 v[10:11], v[0:3], off offset:256
	s_andn2_b64 vcc, exec, s[4:5]
	s_mov_b64 s[4:5], -1
	s_cbranch_vccnz .LBB0_222
